# peel waits relaxed to vmcnt(24) for units>=2 (epilogue stores no longer block next unit start)
# baseline (speedup 1.0000x reference)
.LBB0_178:
	s_and_b32 s12, s6, 3
	s_mov_b64 s[6:7], 0x80
	s_add_i32 m0, s37, 0x18000
	v_lshl_add_u64 v[6:7], v[6:7], 0, s[6:7]
	s_lshl_b32 s9, s8, 13
	s_lshl_b32 s13, s12, 12
	s_waitcnt vmcnt(2)
	s_barrier
	global_load_lds_dwordx4 v[6:7], off
	v_lshl_add_u64 v[4:5], v[4:5], 0, s[6:7]
	s_add_i32 m0, s37, 0x1a000
	s_add_i32 s60, s37, 0x8000
	s_add_i32 s61, s37, 0xa000
	global_load_lds_dwordx4 v[4:5], off
	v_lshl_add_u64 v[0:1], v[0:1], 0, s[6:7]
	s_mov_b32 m0, s60
	s_add_u32 s10, s46, 0x40080
	global_load_lds_dwordx4 v[0:1], off
	v_lshl_add_u64 v[0:1], v[2:3], 0, s[6:7]
	s_mov_b32 m0, s61
	s_addc_u32 s11, s47, 0
	global_load_lds_dwordx4 v[0:1], off
	s_add_i32 m0, s37, 0x1c000
	v_lshl_add_u64 v[0:1], s[10:11], 0, v[130:131]
	global_load_lds_dwordx4 v[0:1], off
	v_lshl_add_u64 v[0:1], s[10:11], 0, v[128:129]
	s_add_i32 m0, s37, 0x1e000
	s_cmpk_lt_u32 s5, 0x100
	global_load_lds_dwordx4 v[0:1], off
	v_bfe_u32 v1, v9, 4, 2
	v_and_b32_e32 v0, 15, v9
	v_lshlrev_b32_e32 v2, 4, v1
	v_lshl_or_b32 v144, s8, 6, v0
	v_lshl_or_b32 v0, v0, 6, v2
	v_lshlrev_b32_e32 v2, 2, v9
	v_and_b32_e32 v2, 32, v2
	v_bitop3_b32 v3, v0, s9, v2 bitop3:0xde
	v_bitop3_b32 v145, v0, s13, v2 bitop3:0xde
	v_lshlrev_b32_e32 v0, 2, v1
	v_lshl_or_b32 v146, s12, 4, v0
	v_lshlrev_b32_e32 v0, 14, v12
	v_and_b32_e32 v0, 0xffff8000, v0
	v_lshl_add_u32 v0, v13, 11, v0
	v_and_b32_e32 v1, 1, v12
	v_lshl_or_b32 v0, v1, 6, v0
	v_lshl_add_u32 v132, v14, 1, v0
	v_lshlrev_b32_e32 v0, 14, v8
	v_and_b32_e32 v0, 0xffff8000, v0
	s_waitcnt vmcnt(6)
	v_lshl_add_u32 v0, v10, 11, v0
	v_and_b32_e32 v1, 1, v8
	s_cselect_b64 s[8:9], -1, 0
	v_lshl_or_b32 v0, v1, 6, v0
	s_add_i32 s62, 0, 0x10000
	s_add_i32 s63, 0, 0x14000
	s_sext_i32_i16 s65, s4
	v_mov_b32_e32 v133, v131
	v_lshl_add_u32 v134, v11, 1, v0
	v_mov_b32_e32 v135, v131
	v_mov_b64_e32 v[136:137], 0xb00
	v_mov_b64_e32 v[138:139], 0xaff
	v_add_u32_e32 v147, s62, v145
	v_add_u32_e32 v148, s63, v145
	v_add_u32_e32 v149, 0, v3
	s_movk_i32 s64, 0x1600
	s_barrier
	s_waitcnt vmcnt(0)
	s_mov_b32 s98, 0
	s_branch .LBB0_181

.LBB0_180:
	s_andn2_b64 vcc, exec, s[4:5]
	s_mov_b32 s65, s10
	s_mov_b32 s36, s12
	s_mov_b64 s[46:47], s[30:31]
	s_mov_b64 s[44:45], s[24:25]
	s_mov_b32 s98, 1
	s_cbranch_vccz .LBB0_190

.LBB0_183:
	s_ashr_i32 s13, s12, 31
	s_lshl_b64 s[24:25], s[12:13], 19
	s_add_u32 s24, s80, s24
	s_addc_u32 s25, s81, s25
	s_and_b64 s[30:31], s[4:5], exec
	s_cselect_b32 s13, s25, s45
	s_cselect_b32 s66, s24, s44
	s_ashr_i32 s11, s10, 31
	s_lshl_b64 s[30:31], s[10:11], 19
	s_add_u32 s30, s52, s30
	s_addc_u32 s31, s53, s31
	s_and_b64 s[48:49], s[4:5], exec
	s_cselect_b32 s11, s31, s47
	s_cselect_b32 s67, s30, s46
	s_add_u32 s44, s44, 0x40080
	s_addc_u32 s45, s45, 0
	s_add_u32 s68, s46, 0x100
	s_addc_u32 s69, s47, 0
	s_mov_b32 s70, -2
	ds_read_b128 v[140:143], v147
	ds_read_b128 v[150:153], v147 offset:1024
	ds_read_b128 v[154:157], v147 offset:2048
	ds_read_b128 v[158:161], v147 offset:3072
	ds_read_b128 v[162:165], v148
	ds_read_b128 v[166:169], v148 offset:1024
	ds_read_b128 v[170:173], v148 offset:2048
	ds_read_b128 v[174:177], v148 offset:3072
	s_add_u32 s18, s44, 0xfffc0080
	s_addc_u32 s19, s45, -1
	s_cmp_eq_u32 s70, 12
	s_cselect_b32 s49, s13, s19
	s_cselect_b32 s48, s66, s18
	s_cselect_b32 s47, s11, s69
	s_cselect_b32 s46, s67, s68
	v_lshl_add_u64 v[178:179], s[44:45], 0, v[132:133]
	s_add_i32 m0, s37, 0xc000
	ds_read_b128 v[184:187], v149
	ds_read_b128 v[188:191], v149 offset:1024
	ds_read_b128 v[192:195], v149 offset:2048
	ds_read_b128 v[196:199], v149 offset:3072
	ds_read_b128 v[200:203], v149 offset:4096
	ds_read_b128 v[204:207], v149 offset:5120
	ds_read_b128 v[208:211], v149 offset:6144
	ds_read_b128 v[212:215], v149 offset:7168
	global_load_lds_dwordx4 v[178:179], off
	v_lshl_add_u64 v[178:179], s[44:45], 0, v[134:135]
	s_add_i32 m0, s37, 0xe000
	s_nop 0
	global_load_lds_dwordx4 v[178:179], off
	s_waitcnt vmcnt(24)
	s_waitcnt lgkmcnt(0)
	s_barrier
	s_setprio 1
	s_waitcnt lgkmcnt(0)
	v_mfma_f32_16x16x32_bf16 v[124:127], v[140:143], v[184:187], 0
	v_mfma_f32_16x16x32_bf16 v[120:123], v[154:157], v[184:187], 0
	v_mfma_f32_16x16x32_bf16 v[108:111], v[140:143], v[192:195], 0
	v_mfma_f32_16x16x32_bf16 v[104:107], v[154:157], v[192:195], 0
	v_mfma_f32_16x16x32_bf16 v[92:95], v[140:143], v[200:203], 0
	v_mfma_f32_16x16x32_bf16 v[88:91], v[154:157], v[200:203], 0
	v_mfma_f32_16x16x32_bf16 v[76:79], v[140:143], v[208:211], 0
	v_mfma_f32_16x16x32_bf16 v[72:75], v[154:157], v[208:211], 0
	v_mfma_f32_16x16x32_bf16 v[124:127], v[150:153], v[188:191], v[124:127]
	v_mfma_f32_16x16x32_bf16 v[120:123], v[158:161], v[188:191], v[120:123]
	v_mfma_f32_16x16x32_bf16 v[108:111], v[150:153], v[196:199], v[108:111]
	v_mfma_f32_16x16x32_bf16 v[104:107], v[158:161], v[196:199], v[104:107]
	v_mfma_f32_16x16x32_bf16 v[92:95], v[150:153], v[204:207], v[92:95]
	v_mfma_f32_16x16x32_bf16 v[88:91], v[158:161], v[204:207], v[88:91]
	v_mfma_f32_16x16x32_bf16 v[76:79], v[150:153], v[212:215], v[76:79]
	v_mfma_f32_16x16x32_bf16 v[72:75], v[158:161], v[212:215], v[72:75]
	s_setprio 0
	s_setprio 1
	v_mfma_f32_16x16x32_bf16 v[116:119], v[162:165], v[184:187], 0
	v_mfma_f32_16x16x32_bf16 v[112:115], v[170:173], v[184:187], 0
	v_mfma_f32_16x16x32_bf16 v[100:103], v[162:165], v[192:195], 0
	v_mfma_f32_16x16x32_bf16 v[96:99], v[170:173], v[192:195], 0
	v_mfma_f32_16x16x32_bf16 v[84:87], v[162:165], v[200:203], 0
	v_mfma_f32_16x16x32_bf16 v[80:83], v[170:173], v[200:203], 0
	v_mfma_f32_16x16x32_bf16 v[68:71], v[162:165], v[208:211], 0
	v_mfma_f32_16x16x32_bf16 v[64:67], v[170:173], v[208:211], 0
	v_mfma_f32_16x16x32_bf16 v[116:119], v[166:169], v[188:191], v[116:119]
	v_mfma_f32_16x16x32_bf16 v[112:115], v[174:177], v[188:191], v[112:115]
	v_mfma_f32_16x16x32_bf16 v[100:103], v[166:169], v[196:199], v[100:103]
	v_mfma_f32_16x16x32_bf16 v[96:99], v[174:177], v[196:199], v[96:99]
	v_mfma_f32_16x16x32_bf16 v[84:87], v[166:169], v[204:207], v[84:87]
	v_mfma_f32_16x16x32_bf16 v[80:83], v[174:177], v[204:207], v[80:83]
	v_mfma_f32_16x16x32_bf16 v[68:71], v[166:169], v[212:215], v[68:71]
	v_mfma_f32_16x16x32_bf16 v[64:67], v[174:177], v[212:215], v[64:67]
	s_setprio 0
	s_barrier
	s_add_i32 s18, s62, s54
	v_lshl_add_u64 v[178:179], s[46:47], 0, v[130:131]
	s_mov_b32 m0, s18
	ds_read_b128 v[184:187], v149 offset:16384
	ds_read_b128 v[188:191], v149 offset:17408
	ds_read_b128 v[192:195], v149 offset:18432
	ds_read_b128 v[196:199], v149 offset:19456
	ds_read_b128 v[200:203], v149 offset:20480
	ds_read_b128 v[204:207], v149 offset:21504
	ds_read_b128 v[208:211], v149 offset:22528
	ds_read_b128 v[212:215], v149 offset:23552
	global_load_lds_dwordx4 v[178:179], off
	s_add_i32 m0, s18, 0x2000
	s_add_u32 s72, s46, 0x40000
	v_lshl_add_u64 v[216:217], s[46:47], 0, v[128:129]
	s_addc_u32 s73, s47, 0
	s_add_i32 s18, s63, s54
	global_load_lds_dwordx4 v[216:217], off
	v_lshl_add_u64 v[218:219], s[72:73], 0, v[130:131]
	s_mov_b32 m0, s18
	v_lshl_add_u64 v[220:221], s[48:49], 0, v[128:129]
	global_load_lds_dwordx4 v[218:219], off
	v_lshl_add_u64 v[218:219], s[72:73], 0, v[128:129]
	s_add_i32 m0, s18, 0x2000
	s_nop 0
	global_load_lds_dwordx4 v[218:219], off
	v_lshl_add_u64 v[218:219], s[48:49], 0, v[130:131]
	s_mov_b32 m0, s37
	s_nop 0
	global_load_lds_dwordx4 v[218:219], off
	s_mov_b32 m0, s56
	s_nop 0
	global_load_lds_dwordx4 v[220:221], off
	s_cmp_eq_u32 s98, 0
	s_cbranch_scc1 .Lpw8_0
	s_waitcnt vmcnt(24)
	s_branch .Lpwj_0
.Lpw8_0:
	s_waitcnt vmcnt(8)
.Lpwj_0:
	s_waitcnt lgkmcnt(0)
	s_barrier
	s_setprio 1
	s_waitcnt lgkmcnt(0)
	v_mfma_f32_16x16x32_bf16 v[60:63], v[140:143], v[184:187], 0
	v_mfma_f32_16x16x32_bf16 v[56:59], v[154:157], v[184:187], 0
	v_mfma_f32_16x16x32_bf16 v[44:47], v[140:143], v[192:195], 0
	v_mfma_f32_16x16x32_bf16 v[40:43], v[154:157], v[192:195], 0
	v_mfma_f32_16x16x32_bf16 v[28:31], v[140:143], v[200:203], 0
	v_mfma_f32_16x16x32_bf16 v[24:27], v[154:157], v[200:203], 0
	v_mfma_f32_16x16x32_bf16 v[12:15], v[140:143], v[208:211], 0
	v_mfma_f32_16x16x32_bf16 v[8:11], v[154:157], v[208:211], 0
	v_mfma_f32_16x16x32_bf16 v[60:63], v[150:153], v[188:191], v[60:63]
	v_mfma_f32_16x16x32_bf16 v[56:59], v[158:161], v[188:191], v[56:59]
	v_mfma_f32_16x16x32_bf16 v[44:47], v[150:153], v[196:199], v[44:47]
	v_mfma_f32_16x16x32_bf16 v[40:43], v[158:161], v[196:199], v[40:43]
	v_mfma_f32_16x16x32_bf16 v[28:31], v[150:153], v[204:207], v[28:31]
	v_mfma_f32_16x16x32_bf16 v[24:27], v[158:161], v[204:207], v[24:27]
	v_mfma_f32_16x16x32_bf16 v[12:15], v[150:153], v[212:215], v[12:15]
	v_mfma_f32_16x16x32_bf16 v[8:11], v[158:161], v[212:215], v[8:11]
	s_setprio 0
	s_setprio 1
	v_mfma_f32_16x16x32_bf16 v[52:55], v[162:165], v[184:187], 0
	v_mfma_f32_16x16x32_bf16 v[48:51], v[170:173], v[184:187], 0
	v_mfma_f32_16x16x32_bf16 v[36:39], v[162:165], v[192:195], 0
	v_mfma_f32_16x16x32_bf16 v[32:35], v[170:173], v[192:195], 0
	v_mfma_f32_16x16x32_bf16 v[20:23], v[162:165], v[200:203], 0
	v_mfma_f32_16x16x32_bf16 v[16:19], v[170:173], v[200:203], 0
	v_mfma_f32_16x16x32_bf16 v[4:7], v[162:165], v[208:211], 0
	v_mfma_f32_16x16x32_bf16 v[0:3], v[170:173], v[208:211], 0
	v_mfma_f32_16x16x32_bf16 v[52:55], v[166:169], v[188:191], v[52:55]
	v_mfma_f32_16x16x32_bf16 v[48:51], v[174:177], v[188:191], v[48:51]
	v_mfma_f32_16x16x32_bf16 v[36:39], v[166:169], v[196:199], v[36:39]
	v_mfma_f32_16x16x32_bf16 v[32:35], v[174:177], v[196:199], v[32:35]
	v_mfma_f32_16x16x32_bf16 v[20:23], v[166:169], v[204:207], v[20:23]
	v_mfma_f32_16x16x32_bf16 v[16:19], v[174:177], v[204:207], v[16:19]
	v_mfma_f32_16x16x32_bf16 v[4:7], v[166:169], v[212:215], v[4:7]
	v_mfma_f32_16x16x32_bf16 v[0:3], v[174:177], v[212:215], v[0:3]
	s_setprio 0
	s_barrier
	s_branch .Lmid_gemm0

.LBB0_250:
	s_lshl_b32 s6, s6, 5
	s_mov_b64 s[8:9], 0x80
	s_and_b32 s18, s6, 0x60
	s_add_i32 m0, s63, 0x18000
	v_lshl_add_u64 v[6:7], v[6:7], 0, s[8:9]
	s_lshl_b32 s11, s7, 13
	s_lshl_b32 s6, s18, 7
	s_waitcnt vmcnt(2)
	s_barrier
	global_load_lds_dwordx4 v[6:7], off
	v_lshl_add_u64 v[4:5], v[4:5], 0, s[8:9]
	s_add_i32 m0, s63, 0x1a000
	s_add_i32 s68, s63, 0x8000
	s_add_i32 s69, s63, 0xa000
	global_load_lds_dwordx4 v[4:5], off
	v_lshl_add_u64 v[0:1], v[0:1], 0, s[8:9]
	s_mov_b32 m0, s68
	s_add_u32 s30, s54, 0xb0080
	global_load_lds_dwordx4 v[0:1], off
	v_lshl_add_u64 v[0:1], v[2:3], 0, s[8:9]
	s_mov_b32 m0, s69
	s_addc_u32 s31, s55, 0
	global_load_lds_dwordx4 v[0:1], off
	s_add_i32 m0, s63, 0x1c000
	v_lshl_add_u64 v[0:1], s[30:31], 0, v[130:131]
	global_load_lds_dwordx4 v[0:1], off
	v_lshl_add_u64 v[0:1], s[30:31], 0, v[134:135]
	s_add_i32 m0, s63, 0x1e000
	s_cmpk_lt_u32 s4, 0x100
	global_load_lds_dwordx4 v[0:1], off
	v_lshrrev_b32_e32 v1, 1, v8
	v_and_b32_e32 v1, 24, v1
	v_and_b32_e32 v0, 15, v8
	v_lshlrev_b32_e32 v2, 1, v1
	v_lshl_or_b32 v146, s7, 6, v0
	v_lshl_or_b32 v0, v0, 6, v2
	v_lshlrev_b32_e32 v2, 2, v8
	v_and_b32_e32 v2, 32, v2
	v_bitop3_b32 v3, v0, s11, v2 bitop3:0xde
	v_bitop3_b32 v147, v0, s6, v2 bitop3:0xde
	v_or_b32_e32 v148, s18, v1
	v_lshrrev_b32_e32 v1, 1, v9
	v_mul_lo_u32 v0, v11, s5
	s_mov_b32 s4, 0xb000
	v_mad_u64_u32 v[0:1], s[30:31], v1, s4, v[0:1]
	v_or_b32_e32 v0, v0, v10
	s_mov_b64 s[6:7], 0xb0080
	v_add_lshl_u32 v0, v0, v12, 1
	v_mov_b32_e32 v1, v131
	v_lshl_add_u64 v[136:137], v[0:1], 0, s[6:7]
	v_lshrrev_b32_e32 v1, 1, v13
	v_mul_lo_u32 v0, v14, s5
	v_mad_u64_u32 v[0:1], s[4:5], v1, s4, v[0:1]
	s_waitcnt vmcnt(6)
	v_or_b32_e32 v0, v0, v15
	s_sext_i32_i8 s83, s10
	s_cselect_b64 s[10:11], -1, 0
	v_add_lshl_u32 v0, v0, v16, 1
	v_mov_b32_e32 v1, v131
	s_add_i32 s70, 0, 0x10000
	s_add_i32 s71, 0, 0x14000
	v_lshl_add_u64 v[138:139], v[0:1], 0, s[6:7]
	v_mov_b64_e32 v[140:141], 0x200
	v_mov_b64_e32 v[142:143], 0x1ff
	v_add_u32_e32 v149, s70, v147
	v_add_u32_e32 v150, s71, v147
	v_add_u32_e32 v151, 0, v3
	s_mov_b64 s[30:31], 0x40000
	s_mov_b32 s72, 0x40000
	s_mov_b64 s[36:37], 0x48000
	s_mov_b32 s73, 0x48000
	s_mov_b64 s[44:45], 0x50000
	s_mov_b32 s74, 0x50000
	s_mov_b64 s[46:47], 0x58000
	s_mov_b32 s75, 0x58000
	s_barrier
	s_mov_b32 s98, 0
	s_branch .LBB0_253

.LBB0_252:
	s_andn2_b64 vcc, exec, s[4:5]
	s_mov_b32 s83, s76
	s_mov_b32 s82, s77
	s_mov_b64 s[54:55], s[48:49]
	s_mov_b64 s[52:53], s[6:7]
	s_mov_b32 s98, 1
	s_cbranch_vccz .LBB0_270

.LBB0_263:
	s_add_u32 s84, s54, 0x100
	s_addc_u32 s85, s55, 0
	s_mov_b32 s86, -2
	ds_read_b128 v[152:155], v149
	ds_read_b128 v[156:159], v149 offset:1024
	ds_read_b128 v[160:163], v149 offset:2048
	ds_read_b128 v[164:167], v149 offset:3072
	ds_read_b128 v[168:171], v150
	ds_read_b128 v[172:175], v150 offset:1024
	ds_read_b128 v[176:179], v150 offset:2048
	ds_read_b128 v[184:187], v150 offset:3072
	s_add_u32 s54, s52, 0x100
	s_addc_u32 s55, s53, 0
	s_cmp_eq_u32 s86, 40
	s_cselect_b32 s59, s7, s55
	s_cselect_b32 s58, s6, s54
	s_cselect_b32 s57, s49, s85
	s_cselect_b32 s56, s48, s84
	v_lshl_add_u64 v[144:145], s[52:53], 0, v[136:137]
	s_add_i32 m0, s63, 0xc000
	ds_read_b128 v[188:191], v151
	ds_read_b128 v[192:195], v151 offset:1024
	ds_read_b128 v[196:199], v151 offset:2048
	ds_read_b128 v[200:203], v151 offset:3072
	ds_read_b128 v[204:207], v151 offset:4096
	ds_read_b128 v[208:211], v151 offset:5120
	ds_read_b128 v[212:215], v151 offset:6144
	ds_read_b128 v[216:219], v151 offset:7168
	global_load_lds_dwordx4 v[144:145], off
	v_lshl_add_u64 v[144:145], s[52:53], 0, v[138:139]
	s_add_i32 m0, s63, 0xe000
	s_nop 0
	global_load_lds_dwordx4 v[144:145], off
	s_waitcnt vmcnt(24)
	s_waitcnt lgkmcnt(0)
	s_barrier
	s_setprio 1
	s_waitcnt lgkmcnt(0)
	v_mfma_f32_16x16x32_bf16 v[124:127], v[152:155], v[188:191], 0
	v_mfma_f32_16x16x32_bf16 v[120:123], v[160:163], v[188:191], 0
	v_mfma_f32_16x16x32_bf16 v[116:119], v[152:155], v[196:199], 0
	v_mfma_f32_16x16x32_bf16 v[108:111], v[160:163], v[196:199], 0
	v_mfma_f32_16x16x32_bf16 v[100:103], v[152:155], v[204:207], 0
	v_mfma_f32_16x16x32_bf16 v[92:95], v[160:163], v[204:207], 0
	v_mfma_f32_16x16x32_bf16 v[84:87], v[152:155], v[212:215], 0
	v_mfma_f32_16x16x32_bf16 v[76:79], v[160:163], v[212:215], 0
	v_mfma_f32_16x16x32_bf16 v[124:127], v[156:159], v[192:195], v[124:127]
	v_mfma_f32_16x16x32_bf16 v[120:123], v[164:167], v[192:195], v[120:123]
	v_mfma_f32_16x16x32_bf16 v[116:119], v[156:159], v[200:203], v[116:119]
	v_mfma_f32_16x16x32_bf16 v[108:111], v[164:167], v[200:203], v[108:111]
	v_mfma_f32_16x16x32_bf16 v[100:103], v[156:159], v[208:211], v[100:103]
	v_mfma_f32_16x16x32_bf16 v[92:95], v[164:167], v[208:211], v[92:95]
	v_mfma_f32_16x16x32_bf16 v[84:87], v[156:159], v[216:219], v[84:87]
	v_mfma_f32_16x16x32_bf16 v[76:79], v[164:167], v[216:219], v[76:79]
	s_setprio 0
	s_setprio 1
	v_mfma_f32_16x16x32_bf16 v[112:115], v[168:171], v[188:191], 0
	v_mfma_f32_16x16x32_bf16 v[104:107], v[176:179], v[188:191], 0
	v_mfma_f32_16x16x32_bf16 v[96:99], v[168:171], v[196:199], 0
	v_mfma_f32_16x16x32_bf16 v[88:91], v[176:179], v[196:199], 0
	v_mfma_f32_16x16x32_bf16 v[80:83], v[168:171], v[204:207], 0
	v_mfma_f32_16x16x32_bf16 v[72:75], v[176:179], v[204:207], 0
	v_mfma_f32_16x16x32_bf16 v[68:71], v[168:171], v[212:215], 0
	v_mfma_f32_16x16x32_bf16 v[64:67], v[176:179], v[212:215], 0
	v_mfma_f32_16x16x32_bf16 v[112:115], v[172:175], v[192:195], v[112:115]
	v_mfma_f32_16x16x32_bf16 v[104:107], v[184:187], v[192:195], v[104:107]
	v_mfma_f32_16x16x32_bf16 v[96:99], v[172:175], v[200:203], v[96:99]
	v_mfma_f32_16x16x32_bf16 v[88:91], v[184:187], v[200:203], v[88:91]
	v_mfma_f32_16x16x32_bf16 v[80:83], v[172:175], v[208:211], v[80:83]
	v_mfma_f32_16x16x32_bf16 v[72:75], v[184:187], v[208:211], v[72:75]
	v_mfma_f32_16x16x32_bf16 v[68:71], v[172:175], v[216:219], v[68:71]
	v_mfma_f32_16x16x32_bf16 v[64:67], v[184:187], v[216:219], v[64:67]
	s_setprio 0
	s_barrier
	s_add_i32 s18, s70, s62
	v_lshl_add_u64 v[144:145], s[56:57], 0, v[130:131]
	s_mov_b32 m0, s18
	ds_read_b128 v[188:191], v151 offset:16384
	ds_read_b128 v[192:195], v151 offset:17408
	ds_read_b128 v[196:199], v151 offset:18432
	ds_read_b128 v[200:203], v151 offset:19456
	ds_read_b128 v[204:207], v151 offset:20480
	ds_read_b128 v[208:211], v151 offset:21504
	ds_read_b128 v[212:215], v151 offset:22528
	ds_read_b128 v[216:219], v151 offset:23552
	global_load_lds_dwordx4 v[144:145], off
	s_add_i32 m0, s18, 0x2000
	s_add_u32 s52, s56, 0xb0000
	v_lshl_add_u64 v[220:221], s[56:57], 0, v[134:135]
	s_addc_u32 s53, s57, 0
	s_add_i32 s18, s71, s62
	global_load_lds_dwordx4 v[220:221], off
	v_lshl_add_u64 v[222:223], s[52:53], 0, v[130:131]
	s_mov_b32 m0, s18
	v_lshl_add_u64 v[224:225], s[58:59], 0, v[132:133]
	global_load_lds_dwordx4 v[222:223], off
	v_lshl_add_u64 v[222:223], s[52:53], 0, v[134:135]
	s_add_i32 m0, s18, 0x2000
	s_nop 0
	global_load_lds_dwordx4 v[222:223], off
	v_lshl_add_u64 v[222:223], s[58:59], 0, v[128:129]
	s_mov_b32 m0, s63
	s_nop 0
	global_load_lds_dwordx4 v[222:223], off
	s_mov_b32 m0, s64
	s_nop 0
	global_load_lds_dwordx4 v[224:225], off
	s_cmp_eq_u32 s98, 0
	s_cbranch_scc1 .Lpw8_1
	s_waitcnt vmcnt(24)
	s_branch .Lpwj_1

.Lpwj_1:
	s_waitcnt lgkmcnt(0)
	s_barrier
	s_setprio 1
	s_waitcnt lgkmcnt(0)
	v_mfma_f32_16x16x32_bf16 v[60:63], v[152:155], v[188:191], 0
	v_mfma_f32_16x16x32_bf16 v[56:59], v[160:163], v[188:191], 0
	v_mfma_f32_16x16x32_bf16 v[52:55], v[152:155], v[196:199], 0
	v_mfma_f32_16x16x32_bf16 v[44:47], v[160:163], v[196:199], 0
	v_mfma_f32_16x16x32_bf16 v[36:39], v[152:155], v[204:207], 0
	v_mfma_f32_16x16x32_bf16 v[28:31], v[160:163], v[204:207], 0
	v_mfma_f32_16x16x32_bf16 v[20:23], v[152:155], v[212:215], 0
	v_mfma_f32_16x16x32_bf16 v[12:15], v[160:163], v[212:215], 0
	v_mfma_f32_16x16x32_bf16 v[60:63], v[156:159], v[192:195], v[60:63]
	v_mfma_f32_16x16x32_bf16 v[56:59], v[164:167], v[192:195], v[56:59]
	v_mfma_f32_16x16x32_bf16 v[52:55], v[156:159], v[200:203], v[52:55]
	v_mfma_f32_16x16x32_bf16 v[44:47], v[164:167], v[200:203], v[44:47]
	v_mfma_f32_16x16x32_bf16 v[36:39], v[156:159], v[208:211], v[36:39]
	v_mfma_f32_16x16x32_bf16 v[28:31], v[164:167], v[208:211], v[28:31]
	v_mfma_f32_16x16x32_bf16 v[20:23], v[156:159], v[216:219], v[20:23]
	v_mfma_f32_16x16x32_bf16 v[12:15], v[164:167], v[216:219], v[12:15]
	s_setprio 0
	s_setprio 1
	v_mfma_f32_16x16x32_bf16 v[48:51], v[168:171], v[188:191], 0
	v_mfma_f32_16x16x32_bf16 v[40:43], v[176:179], v[188:191], 0
	v_mfma_f32_16x16x32_bf16 v[32:35], v[168:171], v[196:199], 0
	v_mfma_f32_16x16x32_bf16 v[24:27], v[176:179], v[196:199], 0
	v_mfma_f32_16x16x32_bf16 v[16:19], v[168:171], v[204:207], 0
	v_mfma_f32_16x16x32_bf16 v[8:11], v[176:179], v[204:207], 0
	v_mfma_f32_16x16x32_bf16 v[4:7], v[168:171], v[212:215], 0
	v_mfma_f32_16x16x32_bf16 v[0:3], v[176:179], v[212:215], 0
	v_mfma_f32_16x16x32_bf16 v[48:51], v[172:175], v[192:195], v[48:51]
	v_mfma_f32_16x16x32_bf16 v[40:43], v[184:187], v[192:195], v[40:43]
	v_mfma_f32_16x16x32_bf16 v[32:35], v[172:175], v[200:203], v[32:35]
	v_mfma_f32_16x16x32_bf16 v[24:27], v[184:187], v[200:203], v[24:27]
	v_mfma_f32_16x16x32_bf16 v[16:19], v[172:175], v[208:211], v[16:19]
	v_mfma_f32_16x16x32_bf16 v[8:11], v[184:187], v[208:211], v[8:11]
	v_mfma_f32_16x16x32_bf16 v[4:7], v[172:175], v[216:219], v[4:7]
	v_mfma_f32_16x16x32_bf16 v[0:3], v[184:187], v[216:219], v[0:3]
	s_setprio 0
	s_barrier
	s_branch .Lmid_gemm1

.LBB0_381:
	s_lshl_b32 s16, s6, 5
	s_mov_b64 s[6:7], 0x80
	s_and_b32 s73, s16, 0x60
	s_add_i32 m0, s68, 0x18000
	v_lshl_add_u64 v[6:7], v[6:7], 0, s[6:7]
	s_lshl_b32 s9, s8, 13
	s_lshl_b32 s17, s73, 7
	s_waitcnt vmcnt(2)
	s_barrier
	global_load_lds_dwordx4 v[6:7], off
	v_lshl_add_u64 v[4:5], v[4:5], 0, s[6:7]
	s_add_i32 m0, s68, 0x1a000
	s_add_i32 s74, s68, 0x8000
	s_add_i32 s75, s68, 0xa000
	global_load_lds_dwordx4 v[4:5], off
	v_lshl_add_u64 v[0:1], v[0:1], 0, s[6:7]
	s_mov_b32 m0, s74
	s_add_u32 s10, s60, 0x40080
	global_load_lds_dwordx4 v[0:1], off
	v_lshl_add_u64 v[0:1], v[2:3], 0, s[6:7]
	s_mov_b32 m0, s75
	s_addc_u32 s11, s61, 0
	global_load_lds_dwordx4 v[0:1], off
	s_add_i32 m0, s68, 0x1c000
	v_lshl_add_u64 v[0:1], s[10:11], 0, v[132:133]
	global_load_lds_dwordx4 v[0:1], off
	v_lshl_add_u64 v[0:1], s[10:11], 0, v[128:129]
	s_add_i32 m0, s68, 0x1e000
	s_cmpk_lt_u32 s5, 0x100
	global_load_lds_dwordx4 v[0:1], off
	v_lshrrev_b32_e32 v1, 1, v9
	v_and_b32_e32 v1, 24, v1
	v_and_b32_e32 v0, 15, v9
	v_lshlrev_b32_e32 v2, 1, v1
	v_lshl_or_b32 v146, s8, 6, v0
	v_lshl_or_b32 v0, v0, 6, v2
	v_lshlrev_b32_e32 v2, 2, v9
	v_and_b32_e32 v2, 32, v2
	v_bitop3_b32 v3, v0, s9, v2 bitop3:0xde
	v_bitop3_b32 v147, v0, s17, v2 bitop3:0xde
	v_and_or_b32 v0, s16, 32, v1
	v_lshlrev_b32_e32 v0, 1, v0
	v_mov_b32_e32 v1, v133
	v_lshl_add_u64 v[136:137], s[22:23], 0, v[0:1]
	v_lshlrev_b32_e32 v0, 14, v13
	v_and_b32_e32 v0, 0xffff8000, v0
	v_lshl_add_u32 v0, v12, 11, v0
	v_and_b32_e32 v1, 1, v13
	v_lshl_or_b32 v0, v1, 6, v0
	v_lshl_add_u32 v138, v14, 1, v0
	v_lshlrev_b32_e32 v0, 14, v8
	v_and_b32_e32 v0, 0xffff8000, v0
	s_waitcnt vmcnt(6)
	v_lshl_add_u32 v0, v10, 11, v0
	v_and_b32_e32 v1, 1, v8
	s_cselect_b64 s[8:9], -1, 0
	v_lshl_or_b32 v0, v1, 6, v0
	s_add_i32 s76, 0, 0x10000
	s_add_i32 s77, 0, 0x14000
	s_sext_i32_i8 s57, s4
	v_mov_b32_e32 v139, v133
	v_lshl_add_u32 v140, v11, 1, v0
	v_mov_b32_e32 v141, v133
	v_mov_b64_e32 v[142:143], 0x600
	v_mov_b64_e32 v[144:145], 0x5ff
	v_add_u32_e32 v148, s76, v147
	v_add_u32_e32 v149, s77, v147
	v_add_u32_e32 v150, 0, v3
	s_mov_b64 s[10:11], 0x4000
	s_mov_b64 s[16:17], 0x4800
	s_mov_b64 s[36:37], 0x5000
	s_mov_b64 s[44:45], 0x5800
	v_mov_b32_e32 v151, 0x3e38aa3b
	s_barrier
	s_mov_b32 s98, 0
	s_branch .LBB0_384

.LBB0_383:
	s_andn2_b64 vcc, exec, s[4:5]
	s_mov_b32 s57, s46
	s_mov_b32 s56, s48
	s_mov_b64 s[60:61], s[54:55]
	s_mov_b64 s[58:59], s[52:53]
	s_mov_b32 s98, 1
	s_cbranch_vccz .LBB0_393

.LBB0_386:
	s_ashr_i32 s49, s48, 31
	s_lshl_b64 s[52:53], s[48:49], 19
	s_add_u32 s52, s80, s52
	s_addc_u32 s53, s81, s53
	s_and_b64 s[54:55], s[4:5], exec
	s_cselect_b32 s49, s53, s59
	s_cselect_b32 s82, s52, s58
	s_ashr_i32 s47, s46, 31
	s_lshl_b64 s[54:55], s[46:47], 19
	s_add_u32 s54, s64, s54
	s_addc_u32 s55, s65, s55
	s_and_b64 s[62:63], s[4:5], exec
	s_cselect_b32 s47, s55, s61
	s_cselect_b32 s83, s54, s60
	s_add_u32 s58, s58, 0x40080
	s_addc_u32 s59, s59, 0
	s_add_u32 s84, s60, 0x100
	s_addc_u32 s85, s61, 0
	s_mov_b32 s86, -2
	ds_read_b128 v[152:155], v148
	ds_read_b128 v[156:159], v148 offset:1024
	ds_read_b128 v[160:163], v148 offset:2048
	ds_read_b128 v[164:167], v148 offset:3072
	ds_read_b128 v[168:171], v149
	ds_read_b128 v[172:175], v149 offset:1024
	ds_read_b128 v[176:179], v149 offset:2048
	ds_read_b128 v[184:187], v149 offset:3072
	s_add_u32 s18, s58, 0xfffc0080
	s_addc_u32 s19, s59, -1
	s_cmp_eq_u32 s86, 12
	s_cselect_b32 s63, s49, s19
	s_cselect_b32 s62, s82, s18
	s_cselect_b32 s61, s47, s85
	s_cselect_b32 s60, s83, s84
	v_lshl_add_u64 v[220:221], s[58:59], 0, v[138:139]
	s_add_i32 m0, s68, 0xc000
	ds_read_b128 v[188:191], v150
	ds_read_b128 v[192:195], v150 offset:1024
	ds_read_b128 v[196:199], v150 offset:2048
	ds_read_b128 v[200:203], v150 offset:3072
	ds_read_b128 v[204:207], v150 offset:4096
	ds_read_b128 v[208:211], v150 offset:5120
	ds_read_b128 v[212:215], v150 offset:6144
	ds_read_b128 v[216:219], v150 offset:7168
	global_load_lds_dwordx4 v[220:221], off
	v_lshl_add_u64 v[220:221], s[58:59], 0, v[140:141]
	s_add_i32 m0, s68, 0xe000
	s_nop 0
	global_load_lds_dwordx4 v[220:221], off
	s_waitcnt vmcnt(24)
	s_waitcnt lgkmcnt(0)
	s_barrier
	s_setprio 1
	s_waitcnt lgkmcnt(0)
	v_mfma_f32_16x16x32_bf16 v[124:127], v[152:155], v[188:191], 0
	v_mfma_f32_16x16x32_bf16 v[120:123], v[160:163], v[188:191], 0
	v_mfma_f32_16x16x32_bf16 v[116:119], v[152:155], v[196:199], 0
	v_mfma_f32_16x16x32_bf16 v[112:115], v[160:163], v[196:199], 0
	v_mfma_f32_16x16x32_bf16 v[108:111], v[152:155], v[204:207], 0
	v_mfma_f32_16x16x32_bf16 v[104:107], v[160:163], v[204:207], 0
	v_mfma_f32_16x16x32_bf16 v[100:103], v[152:155], v[212:215], 0
	v_mfma_f32_16x16x32_bf16 v[96:99], v[160:163], v[212:215], 0
	v_mfma_f32_16x16x32_bf16 v[124:127], v[156:159], v[192:195], v[124:127]
	v_mfma_f32_16x16x32_bf16 v[120:123], v[164:167], v[192:195], v[120:123]
	v_mfma_f32_16x16x32_bf16 v[116:119], v[156:159], v[200:203], v[116:119]
	v_mfma_f32_16x16x32_bf16 v[112:115], v[164:167], v[200:203], v[112:115]
	v_mfma_f32_16x16x32_bf16 v[108:111], v[156:159], v[208:211], v[108:111]
	v_mfma_f32_16x16x32_bf16 v[104:107], v[164:167], v[208:211], v[104:107]
	v_mfma_f32_16x16x32_bf16 v[100:103], v[156:159], v[216:219], v[100:103]
	v_mfma_f32_16x16x32_bf16 v[96:99], v[164:167], v[216:219], v[96:99]
	s_setprio 0
	s_setprio 1
	v_mfma_f32_16x16x32_bf16 v[68:71], v[168:171], v[188:191], 0
	v_mfma_f32_16x16x32_bf16 v[64:67], v[176:179], v[188:191], 0
	v_mfma_f32_16x16x32_bf16 v[52:55], v[168:171], v[196:199], 0
	v_mfma_f32_16x16x32_bf16 v[48:51], v[176:179], v[196:199], 0
	v_mfma_f32_16x16x32_bf16 v[44:47], v[168:171], v[204:207], 0
	v_mfma_f32_16x16x32_bf16 v[40:43], v[176:179], v[204:207], 0
	v_mfma_f32_16x16x32_bf16 v[36:39], v[168:171], v[212:215], 0
	v_mfma_f32_16x16x32_bf16 v[32:35], v[176:179], v[212:215], 0
	v_mfma_f32_16x16x32_bf16 v[68:71], v[172:175], v[192:195], v[68:71]
	v_mfma_f32_16x16x32_bf16 v[64:67], v[184:187], v[192:195], v[64:67]
	v_mfma_f32_16x16x32_bf16 v[52:55], v[172:175], v[200:203], v[52:55]
	v_mfma_f32_16x16x32_bf16 v[48:51], v[184:187], v[200:203], v[48:51]
	v_mfma_f32_16x16x32_bf16 v[44:47], v[172:175], v[208:211], v[44:47]
	v_mfma_f32_16x16x32_bf16 v[40:43], v[184:187], v[208:211], v[40:43]
	v_mfma_f32_16x16x32_bf16 v[36:39], v[172:175], v[216:219], v[36:39]
	v_mfma_f32_16x16x32_bf16 v[32:35], v[184:187], v[216:219], v[32:35]
	s_setprio 0
	s_barrier
	s_add_i32 s18, s76, s66
	v_lshl_add_u64 v[220:221], s[60:61], 0, v[132:133]
	s_mov_b32 m0, s18
	ds_read_b128 v[188:191], v150 offset:16384
	ds_read_b128 v[192:195], v150 offset:17408
	ds_read_b128 v[196:199], v150 offset:18432
	ds_read_b128 v[200:203], v150 offset:19456
	ds_read_b128 v[204:207], v150 offset:20480
	ds_read_b128 v[208:211], v150 offset:21504
	ds_read_b128 v[212:215], v150 offset:22528
	ds_read_b128 v[216:219], v150 offset:23552
	global_load_lds_dwordx4 v[220:221], off
	s_add_i32 m0, s18, 0x2000
	s_add_u32 s88, s60, 0x40000
	v_lshl_add_u64 v[222:223], s[60:61], 0, v[128:129]
	s_addc_u32 s89, s61, 0
	s_add_i32 s18, s77, s66
	global_load_lds_dwordx4 v[222:223], off
	v_lshl_add_u64 v[224:225], s[88:89], 0, v[132:133]
	s_mov_b32 m0, s18
	v_lshl_add_u64 v[226:227], s[62:63], 0, v[130:131]
	global_load_lds_dwordx4 v[224:225], off
	v_lshl_add_u64 v[224:225], s[88:89], 0, v[128:129]
	s_add_i32 m0, s18, 0x2000
	s_nop 0
	global_load_lds_dwordx4 v[224:225], off
	v_lshl_add_u64 v[224:225], s[62:63], 0, v[134:135]
	s_mov_b32 m0, s68
	s_nop 0
	global_load_lds_dwordx4 v[224:225], off
	s_mov_b32 m0, s69
	s_nop 0
	global_load_lds_dwordx4 v[226:227], off
	s_cmp_eq_u32 s98, 0
	s_cbranch_scc1 .Lpw8_2
	s_waitcnt vmcnt(24)
	s_branch .Lpwj_2

.Lpwj_2:
	s_waitcnt lgkmcnt(0)
	s_barrier
	s_setprio 1
	s_waitcnt lgkmcnt(0)
	v_mfma_f32_16x16x32_bf16 v[92:95], v[152:155], v[188:191], 0
	v_mfma_f32_16x16x32_bf16 v[88:91], v[160:163], v[188:191], 0
	v_mfma_f32_16x16x32_bf16 v[84:87], v[152:155], v[196:199], 0
	v_mfma_f32_16x16x32_bf16 v[80:83], v[160:163], v[196:199], 0
	v_mfma_f32_16x16x32_bf16 v[76:79], v[152:155], v[204:207], 0
	v_mfma_f32_16x16x32_bf16 v[72:75], v[160:163], v[204:207], 0
	v_mfma_f32_16x16x32_bf16 v[60:63], v[152:155], v[212:215], 0
	v_mfma_f32_16x16x32_bf16 v[56:59], v[160:163], v[212:215], 0
	v_mfma_f32_16x16x32_bf16 v[92:95], v[156:159], v[192:195], v[92:95]
	v_mfma_f32_16x16x32_bf16 v[88:91], v[164:167], v[192:195], v[88:91]
	v_mfma_f32_16x16x32_bf16 v[84:87], v[156:159], v[200:203], v[84:87]
	v_mfma_f32_16x16x32_bf16 v[80:83], v[164:167], v[200:203], v[80:83]
	v_mfma_f32_16x16x32_bf16 v[76:79], v[156:159], v[208:211], v[76:79]
	v_mfma_f32_16x16x32_bf16 v[72:75], v[164:167], v[208:211], v[72:75]
	v_mfma_f32_16x16x32_bf16 v[60:63], v[156:159], v[216:219], v[60:63]
	v_mfma_f32_16x16x32_bf16 v[56:59], v[164:167], v[216:219], v[56:59]
	s_setprio 0
	s_setprio 1
	v_mfma_f32_16x16x32_bf16 v[28:31], v[168:171], v[188:191], 0
	v_mfma_f32_16x16x32_bf16 v[24:27], v[176:179], v[188:191], 0
	v_mfma_f32_16x16x32_bf16 v[20:23], v[168:171], v[196:199], 0
	v_mfma_f32_16x16x32_bf16 v[16:19], v[176:179], v[196:199], 0
	v_mfma_f32_16x16x32_bf16 v[12:15], v[168:171], v[204:207], 0
	v_mfma_f32_16x16x32_bf16 v[8:11], v[176:179], v[204:207], 0
	v_mfma_f32_16x16x32_bf16 v[4:7], v[168:171], v[212:215], 0
	v_mfma_f32_16x16x32_bf16 v[0:3], v[176:179], v[212:215], 0
	v_mfma_f32_16x16x32_bf16 v[28:31], v[172:175], v[192:195], v[28:31]
	v_mfma_f32_16x16x32_bf16 v[24:27], v[184:187], v[192:195], v[24:27]
	v_mfma_f32_16x16x32_bf16 v[20:23], v[172:175], v[200:203], v[20:23]
	v_mfma_f32_16x16x32_bf16 v[16:19], v[184:187], v[200:203], v[16:19]
	v_mfma_f32_16x16x32_bf16 v[12:15], v[172:175], v[208:211], v[12:15]
	v_mfma_f32_16x16x32_bf16 v[8:11], v[184:187], v[208:211], v[8:11]
	v_mfma_f32_16x16x32_bf16 v[4:7], v[172:175], v[216:219], v[4:7]
	v_mfma_f32_16x16x32_bf16 v[0:3], v[184:187], v[216:219], v[0:3]
	s_setprio 0
	s_barrier
	s_branch .Lmid_gemm2

.LBB0_591:
	s_lshl_b32 s10, s10, 5
	s_and_b32 s18, s10, 0x60
	s_mov_b64 s[10:11], 0x80
	s_add_i32 m0, s57, 0x18000
	v_lshl_add_u64 v[6:7], v[6:7], 0, s[10:11]
	s_lshl_b32 s13, s12, 13
	s_lshl_b32 s19, s18, 7
	s_waitcnt vmcnt(2)
	s_barrier
	global_load_lds_dwordx4 v[6:7], off
	v_lshl_add_u64 v[2:3], v[2:3], 0, s[10:11]
	s_add_i32 m0, s57, 0x1a000
	s_add_i32 s71, s57, 0x8000
	s_add_i32 s72, s57, 0xa000
	global_load_lds_dwordx4 v[2:3], off
	v_lshl_add_u64 v[0:1], v[0:1], 0, s[10:11]
	s_mov_b32 m0, s71
	s_add_u32 s16, s60, 0x40080
	global_load_lds_dwordx4 v[0:1], off
	v_lshl_add_u64 v[0:1], v[4:5], 0, s[10:11]
	s_mov_b32 m0, s72
	s_addc_u32 s17, s61, 0
	global_load_lds_dwordx4 v[0:1], off
	s_add_i32 m0, s57, 0x1c000
	v_lshl_add_u64 v[0:1], s[16:17], 0, v[130:131]
	global_load_lds_dwordx4 v[0:1], off
	v_lshl_add_u64 v[0:1], s[16:17], 0, v[134:135]
	s_add_i32 m0, s57, 0x1e000
	s_cmpk_lt_u32 s5, 0x100
	global_load_lds_dwordx4 v[0:1], off
	v_lshrrev_b32_e32 v1, 1, v8
	v_and_b32_e32 v1, 24, v1
	v_and_b32_e32 v0, 15, v8
	v_lshlrev_b32_e32 v2, 1, v1
	v_lshl_or_b32 v146, s12, 6, v0
	v_lshl_or_b32 v0, v0, 6, v2
	v_lshlrev_b32_e32 v2, 2, v8
	v_and_b32_e32 v2, 32, v2
	v_bitop3_b32 v3, v0, s13, v2 bitop3:0xde
	v_bitop3_b32 v147, v0, s19, v2 bitop3:0xde
	v_lshlrev_b32_e32 v0, 14, v9
	v_and_b32_e32 v0, 0xffff8000, v0
	v_or_b32_e32 v148, s18, v1
	v_lshl_add_u32 v0, v10, 11, v0
	v_and_b32_e32 v1, 1, v9
	v_lshl_or_b32 v0, v1, 6, v0
	v_lshl_add_u32 v136, v11, 1, v0
	v_lshlrev_b32_e32 v0, 14, v12
	v_and_b32_e32 v0, 0xffff8000, v0
	s_waitcnt vmcnt(6)
	v_lshl_add_u32 v0, v13, 11, v0
	v_and_b32_e32 v1, 1, v12
	s_cselect_b64 s[12:13], -1, 0
	v_lshl_or_b32 v0, v1, 6, v0
	s_add_i32 s73, 0, 0x10000
	s_add_i32 s74, 0, 0x14000
	s_sext_i32_i8 s83, s4
	v_mov_b32_e32 v137, v131
	v_lshl_add_u32 v138, v14, 1, v0
	v_mov_b32_e32 v139, v131
	v_mov_b64_e32 v[140:141], 0x200
	v_mov_b64_e32 v[142:143], 0x1ff
	v_add_u32_e32 v149, s73, v147
	v_add_u32_e32 v150, s74, v147
	v_add_u32_e32 v151, 0, v3
	s_mov_b32 s75, 0x40000
	s_mov_b64 s[16:17], 0x48000
	s_mov_b32 s76, 0x48000
	s_mov_b64 s[36:37], 0x50000
	s_mov_b32 s77, 0x50000
	s_mov_b64 s[44:45], 0x58000
	s_mov_b32 s82, 0x58000
	s_barrier
	s_mov_b32 s98, 0
	s_branch .LBB0_594

.LBB0_593:
	s_andn2_b64 vcc, exec, s[4:5]
	s_mov_b32 s83, s46
	s_mov_b32 s56, s48
	s_mov_b64 s[60:61], s[54:55]
	s_mov_b64 s[58:59], s[52:53]
	s_mov_b32 s98, 1
	s_cbranch_vccz .LBB0_607

.LBB0_600:
	s_ashr_i32 s49, s48, 31
	s_lshl_b64 s[18:19], s[48:49], 19
	s_add_u32 s52, s38, s18
	s_addc_u32 s53, s39, s19
	s_and_b64 s[18:19], s[4:5], exec
	s_cselect_b32 s49, s53, s59
	s_cselect_b32 s84, s52, s58
	s_ashr_i32 s47, s46, 31
	s_lshl_b64 s[18:19], s[46:47], 19
	s_add_u32 s54, s64, s18
	s_addc_u32 s55, s65, s19
	s_and_b64 s[18:19], s[4:5], exec
	s_cselect_b32 s47, s55, s61
	s_cselect_b32 s85, s54, s60
	s_add_u32 s58, s58, 0x40080
	s_addc_u32 s59, s59, 0
	s_add_u32 s86, s60, 0x100
	s_addc_u32 s87, s61, 0
	s_mov_b32 s88, -2
	ds_read_b128 v[152:155], v149
	ds_read_b128 v[156:159], v149 offset:1024
	ds_read_b128 v[160:163], v149 offset:2048
	ds_read_b128 v[164:167], v149 offset:3072
	ds_read_b128 v[168:171], v150
	ds_read_b128 v[172:175], v150 offset:1024
	ds_read_b128 v[176:179], v150 offset:2048
	ds_read_b128 v[184:187], v150 offset:3072
	s_add_u32 s18, s58, 0xfffc0080
	s_addc_u32 s19, s59, -1
	s_cmp_eq_u32 s88, 12
	s_cselect_b32 s63, s49, s19
	s_cselect_b32 s62, s84, s18
	s_cselect_b32 s61, s47, s87
	s_cselect_b32 s60, s85, s86
	v_lshl_add_u64 v[144:145], s[58:59], 0, v[136:137]
	s_add_i32 m0, s57, 0xc000
	ds_read_b128 v[188:191], v151
	ds_read_b128 v[192:195], v151 offset:1024
	ds_read_b128 v[196:199], v151 offset:2048
	ds_read_b128 v[200:203], v151 offset:3072
	ds_read_b128 v[204:207], v151 offset:4096
	ds_read_b128 v[208:211], v151 offset:5120
	ds_read_b128 v[212:215], v151 offset:6144
	ds_read_b128 v[216:219], v151 offset:7168
	global_load_lds_dwordx4 v[144:145], off
	v_lshl_add_u64 v[144:145], s[58:59], 0, v[138:139]
	s_add_i32 m0, s57, 0xe000
	s_nop 0
	global_load_lds_dwordx4 v[144:145], off
	s_waitcnt vmcnt(24)
	s_waitcnt lgkmcnt(0)
	s_barrier
	s_setprio 1
	s_waitcnt lgkmcnt(0)
	v_mfma_f32_16x16x32_bf16 v[124:127], v[152:155], v[188:191], 0
	v_mfma_f32_16x16x32_bf16 v[120:123], v[160:163], v[188:191], 0
	v_mfma_f32_16x16x32_bf16 v[116:119], v[152:155], v[196:199], 0
	v_mfma_f32_16x16x32_bf16 v[108:111], v[160:163], v[196:199], 0
	v_mfma_f32_16x16x32_bf16 v[100:103], v[152:155], v[204:207], 0
	v_mfma_f32_16x16x32_bf16 v[92:95], v[160:163], v[204:207], 0
	v_mfma_f32_16x16x32_bf16 v[84:87], v[152:155], v[212:215], 0
	v_mfma_f32_16x16x32_bf16 v[76:79], v[160:163], v[212:215], 0
	v_mfma_f32_16x16x32_bf16 v[124:127], v[156:159], v[192:195], v[124:127]
	v_mfma_f32_16x16x32_bf16 v[120:123], v[164:167], v[192:195], v[120:123]
	v_mfma_f32_16x16x32_bf16 v[116:119], v[156:159], v[200:203], v[116:119]
	v_mfma_f32_16x16x32_bf16 v[108:111], v[164:167], v[200:203], v[108:111]
	v_mfma_f32_16x16x32_bf16 v[100:103], v[156:159], v[208:211], v[100:103]
	v_mfma_f32_16x16x32_bf16 v[92:95], v[164:167], v[208:211], v[92:95]
	v_mfma_f32_16x16x32_bf16 v[84:87], v[156:159], v[216:219], v[84:87]
	v_mfma_f32_16x16x32_bf16 v[76:79], v[164:167], v[216:219], v[76:79]
	s_setprio 0
	s_setprio 1
	v_mfma_f32_16x16x32_bf16 v[112:115], v[168:171], v[188:191], 0
	v_mfma_f32_16x16x32_bf16 v[104:107], v[176:179], v[188:191], 0
	v_mfma_f32_16x16x32_bf16 v[96:99], v[168:171], v[196:199], 0
	v_mfma_f32_16x16x32_bf16 v[88:91], v[176:179], v[196:199], 0
	v_mfma_f32_16x16x32_bf16 v[80:83], v[168:171], v[204:207], 0
	v_mfma_f32_16x16x32_bf16 v[72:75], v[176:179], v[204:207], 0
	v_mfma_f32_16x16x32_bf16 v[68:71], v[168:171], v[212:215], 0
	v_mfma_f32_16x16x32_bf16 v[64:67], v[176:179], v[212:215], 0
	v_mfma_f32_16x16x32_bf16 v[112:115], v[172:175], v[192:195], v[112:115]
	v_mfma_f32_16x16x32_bf16 v[104:107], v[184:187], v[192:195], v[104:107]
	v_mfma_f32_16x16x32_bf16 v[96:99], v[172:175], v[200:203], v[96:99]
	v_mfma_f32_16x16x32_bf16 v[88:91], v[184:187], v[200:203], v[88:91]
	v_mfma_f32_16x16x32_bf16 v[80:83], v[172:175], v[208:211], v[80:83]
	v_mfma_f32_16x16x32_bf16 v[72:75], v[184:187], v[208:211], v[72:75]
	v_mfma_f32_16x16x32_bf16 v[68:71], v[172:175], v[216:219], v[68:71]
	v_mfma_f32_16x16x32_bf16 v[64:67], v[184:187], v[216:219], v[64:67]
	s_setprio 0
	s_barrier
	s_add_i32 s18, s73, s66
	v_lshl_add_u64 v[144:145], s[60:61], 0, v[130:131]
	s_mov_b32 m0, s18
	ds_read_b128 v[188:191], v151 offset:16384
	ds_read_b128 v[192:195], v151 offset:17408
	ds_read_b128 v[196:199], v151 offset:18432
	ds_read_b128 v[200:203], v151 offset:19456
	ds_read_b128 v[204:207], v151 offset:20480
	ds_read_b128 v[208:211], v151 offset:21504
	ds_read_b128 v[212:215], v151 offset:22528
	ds_read_b128 v[216:219], v151 offset:23552
	global_load_lds_dwordx4 v[144:145], off
	s_add_i32 m0, s18, 0x2000
	s_add_u32 s18, s60, 0x40000
	v_lshl_add_u64 v[220:221], s[60:61], 0, v[134:135]
	s_addc_u32 s19, s61, 0
	s_add_i32 s79, s74, s66
	global_load_lds_dwordx4 v[220:221], off
	v_lshl_add_u64 v[222:223], s[18:19], 0, v[130:131]
	s_mov_b32 m0, s79
	v_lshl_add_u64 v[224:225], s[62:63], 0, v[132:133]
	global_load_lds_dwordx4 v[222:223], off
	v_lshl_add_u64 v[222:223], s[18:19], 0, v[134:135]
	s_add_i32 m0, s79, 0x2000
	s_nop 0
	global_load_lds_dwordx4 v[222:223], off
	v_lshl_add_u64 v[222:223], s[62:63], 0, v[128:129]
	s_mov_b32 m0, s57
	s_nop 0
	global_load_lds_dwordx4 v[222:223], off
	s_mov_b32 m0, s67
	s_nop 0
	global_load_lds_dwordx4 v[224:225], off
	s_cmp_eq_u32 s98, 0
	s_cbranch_scc1 .Lpw8_3
	s_waitcnt vmcnt(24)
	s_branch .Lpwj_3

.LBB0_718:
	s_and_b32 s30, s12, 3
	s_mov_b64 s[12:13], 0x80
	s_add_i32 m0, s47, 0x18000
	v_lshl_add_u64 v[6:7], v[6:7], 0, s[12:13]
	s_lshl_b32 s17, s16, 13
	s_lshl_b32 s31, s30, 12
	s_waitcnt vmcnt(2)
	s_barrier
	global_load_lds_dwordx4 v[6:7], off
	v_lshl_add_u64 v[4:5], v[4:5], 0, s[12:13]
	s_add_i32 m0, s47, 0x1a000
	s_add_i32 s64, s47, 0x8000
	s_add_i32 s65, s47, 0xa000
	global_load_lds_dwordx4 v[4:5], off
	v_lshl_add_u64 v[0:1], v[0:1], 0, s[12:13]
	s_mov_b32 m0, s64
	s_add_u32 s18, s52, 0x40080
	global_load_lds_dwordx4 v[0:1], off
	v_lshl_add_u64 v[0:1], v[2:3], 0, s[12:13]
	s_mov_b32 m0, s65
	s_addc_u32 s19, s53, 0
	global_load_lds_dwordx4 v[0:1], off
	s_add_i32 m0, s47, 0x1c000
	v_lshl_add_u64 v[0:1], s[18:19], 0, v[130:131]
	global_load_lds_dwordx4 v[0:1], off
	v_lshl_add_u64 v[0:1], s[18:19], 0, v[128:129]
	s_add_i32 m0, s47, 0x1e000
	s_cmpk_lt_u32 s11, 0x100
	global_load_lds_dwordx4 v[0:1], off
	v_bfe_u32 v1, v9, 4, 2
	v_and_b32_e32 v0, 15, v9
	v_lshlrev_b32_e32 v2, 4, v1
	v_lshl_or_b32 v144, s16, 6, v0
	v_lshl_or_b32 v0, v0, 6, v2
	v_lshlrev_b32_e32 v2, 2, v9
	v_and_b32_e32 v2, 32, v2
	v_bitop3_b32 v3, v0, s17, v2 bitop3:0xde
	v_bitop3_b32 v145, v0, s31, v2 bitop3:0xde
	v_lshlrev_b32_e32 v0, 2, v1
	v_lshl_or_b32 v146, s30, 4, v0
	v_lshlrev_b32_e32 v0, 14, v12
	v_and_b32_e32 v0, 0xffff8000, v0
	v_lshl_add_u32 v0, v13, 11, v0
	v_and_b32_e32 v1, 1, v12
	v_lshl_or_b32 v0, v1, 6, v0
	v_lshl_add_u32 v132, v14, 1, v0
	v_lshlrev_b32_e32 v0, 14, v8
	v_and_b32_e32 v0, 0xffff8000, v0
	s_waitcnt vmcnt(6)
	v_lshl_add_u32 v0, v10, 11, v0
	v_and_b32_e32 v1, 1, v8
	s_cselect_b64 s[16:17], -1, 0
	v_lshl_or_b32 v0, v1, 6, v0
	s_add_i32 s66, 0, 0x10000
	s_add_i32 s67, 0, 0x14000
	s_sext_i32_i16 s69, s10
	v_mov_b32_e32 v133, v131
	v_lshl_add_u32 v134, v11, 1, v0
	v_mov_b32_e32 v135, v131
	v_mov_b64_e32 v[136:137], 0xb00
	v_mov_b64_e32 v[138:139], 0xaff
	v_add_u32_e32 v147, s66, v145
	v_add_u32_e32 v148, s67, v145
	v_add_u32_e32 v149, 0, v3
	s_movk_i32 s68, 0x1600
	s_barrier
	s_mov_b32 s98, 0
	s_branch .LBB0_721

.LBB0_720:
	s_andn2_b64 vcc, exec, s[10:11]
	s_mov_b32 s69, s18
	s_mov_b32 s46, s30
	s_mov_b64 s[52:53], s[44:45]
	s_mov_b64 s[48:49], s[36:37]
	s_mov_b32 s98, 1
	s_cbranch_vccz .LBB0_730

.LBB0_723:
	s_ashr_i32 s31, s30, 31
	s_lshl_b64 s[36:37], s[30:31], 19
	s_add_u32 s36, s80, s36
	s_addc_u32 s37, s81, s37
	s_and_b64 s[44:45], s[10:11], exec
	s_cselect_b32 s31, s37, s49
	s_cselect_b32 s70, s36, s48
	s_ashr_i32 s19, s18, 31
	s_lshl_b64 s[44:45], s[18:19], 19
	s_add_u32 s44, s56, s44
	s_addc_u32 s45, s57, s45
	s_and_b64 s[54:55], s[10:11], exec
	s_cselect_b32 s19, s45, s53
	s_cselect_b32 s71, s44, s52
	s_add_u32 s48, s48, 0x40080
	s_addc_u32 s49, s49, 0
	s_add_u32 s72, s52, 0x100
	s_addc_u32 s73, s53, 0
	s_mov_b32 s74, -2
	ds_read_b128 v[140:143], v147
	ds_read_b128 v[150:153], v147 offset:1024
	ds_read_b128 v[154:157], v147 offset:2048
	ds_read_b128 v[158:161], v147 offset:3072
	ds_read_b128 v[162:165], v148
	ds_read_b128 v[166:169], v148 offset:1024
	ds_read_b128 v[170:173], v148 offset:2048
	ds_read_b128 v[174:177], v148 offset:3072
	s_add_u32 s52, s48, 0xfffc0080
	s_addc_u32 s53, s49, -1
	s_cmp_eq_u32 s74, 12
	s_cselect_b32 s55, s31, s53
	s_cselect_b32 s54, s70, s52
	s_cselect_b32 s53, s19, s73
	s_cselect_b32 s52, s71, s72
	v_lshl_add_u64 v[178:179], s[48:49], 0, v[132:133]
	s_add_i32 m0, s47, 0xc000
	ds_read_b128 v[184:187], v149
	ds_read_b128 v[188:191], v149 offset:1024
	ds_read_b128 v[192:195], v149 offset:2048
	ds_read_b128 v[196:199], v149 offset:3072
	ds_read_b128 v[200:203], v149 offset:4096
	ds_read_b128 v[204:207], v149 offset:5120
	ds_read_b128 v[208:211], v149 offset:6144
	ds_read_b128 v[212:215], v149 offset:7168
	global_load_lds_dwordx4 v[178:179], off
	v_lshl_add_u64 v[178:179], s[48:49], 0, v[134:135]
	s_add_i32 m0, s47, 0xe000
	s_nop 0
	global_load_lds_dwordx4 v[178:179], off
	s_waitcnt vmcnt(24)
	s_waitcnt lgkmcnt(0)
	s_barrier
	s_setprio 1
	s_waitcnt lgkmcnt(0)
	v_mfma_f32_16x16x32_bf16 v[124:127], v[140:143], v[184:187], 0
	v_mfma_f32_16x16x32_bf16 v[120:123], v[154:157], v[184:187], 0
	v_mfma_f32_16x16x32_bf16 v[108:111], v[140:143], v[192:195], 0
	v_mfma_f32_16x16x32_bf16 v[104:107], v[154:157], v[192:195], 0
	v_mfma_f32_16x16x32_bf16 v[92:95], v[140:143], v[200:203], 0
	v_mfma_f32_16x16x32_bf16 v[88:91], v[154:157], v[200:203], 0
	v_mfma_f32_16x16x32_bf16 v[76:79], v[140:143], v[208:211], 0
	v_mfma_f32_16x16x32_bf16 v[72:75], v[154:157], v[208:211], 0
	v_mfma_f32_16x16x32_bf16 v[124:127], v[150:153], v[188:191], v[124:127]
	v_mfma_f32_16x16x32_bf16 v[120:123], v[158:161], v[188:191], v[120:123]
	v_mfma_f32_16x16x32_bf16 v[108:111], v[150:153], v[196:199], v[108:111]
	v_mfma_f32_16x16x32_bf16 v[104:107], v[158:161], v[196:199], v[104:107]
	v_mfma_f32_16x16x32_bf16 v[92:95], v[150:153], v[204:207], v[92:95]
	v_mfma_f32_16x16x32_bf16 v[88:91], v[158:161], v[204:207], v[88:91]
	v_mfma_f32_16x16x32_bf16 v[76:79], v[150:153], v[212:215], v[76:79]
	v_mfma_f32_16x16x32_bf16 v[72:75], v[158:161], v[212:215], v[72:75]
	s_setprio 0
	s_setprio 1
	v_mfma_f32_16x16x32_bf16 v[116:119], v[162:165], v[184:187], 0
	v_mfma_f32_16x16x32_bf16 v[112:115], v[170:173], v[184:187], 0
	v_mfma_f32_16x16x32_bf16 v[100:103], v[162:165], v[192:195], 0
	v_mfma_f32_16x16x32_bf16 v[96:99], v[170:173], v[192:195], 0
	v_mfma_f32_16x16x32_bf16 v[84:87], v[162:165], v[200:203], 0
	v_mfma_f32_16x16x32_bf16 v[80:83], v[170:173], v[200:203], 0
	v_mfma_f32_16x16x32_bf16 v[68:71], v[162:165], v[208:211], 0
	v_mfma_f32_16x16x32_bf16 v[64:67], v[170:173], v[208:211], 0
	v_mfma_f32_16x16x32_bf16 v[116:119], v[166:169], v[188:191], v[116:119]
	v_mfma_f32_16x16x32_bf16 v[112:115], v[174:177], v[188:191], v[112:115]
	v_mfma_f32_16x16x32_bf16 v[100:103], v[166:169], v[196:199], v[100:103]
	v_mfma_f32_16x16x32_bf16 v[96:99], v[174:177], v[196:199], v[96:99]
	v_mfma_f32_16x16x32_bf16 v[84:87], v[166:169], v[204:207], v[84:87]
	v_mfma_f32_16x16x32_bf16 v[80:83], v[174:177], v[204:207], v[80:83]
	v_mfma_f32_16x16x32_bf16 v[68:71], v[166:169], v[212:215], v[68:71]
	v_mfma_f32_16x16x32_bf16 v[64:67], v[174:177], v[212:215], v[64:67]
	s_setprio 0
	s_barrier
	s_add_i32 s75, s66, s58
	v_lshl_add_u64 v[178:179], s[52:53], 0, v[130:131]
	s_mov_b32 m0, s75
	ds_read_b128 v[184:187], v149 offset:16384
	ds_read_b128 v[188:191], v149 offset:17408
	ds_read_b128 v[192:195], v149 offset:18432
	ds_read_b128 v[196:199], v149 offset:19456
	ds_read_b128 v[200:203], v149 offset:20480
	ds_read_b128 v[204:207], v149 offset:21504
	ds_read_b128 v[208:211], v149 offset:22528
	ds_read_b128 v[212:215], v149 offset:23552
	global_load_lds_dwordx4 v[178:179], off
	s_add_i32 m0, s75, 0x2000
	s_add_u32 s76, s52, 0x40000
	v_lshl_add_u64 v[216:217], s[52:53], 0, v[128:129]
	s_addc_u32 s77, s53, 0
	s_add_i32 s75, s67, s58
	global_load_lds_dwordx4 v[216:217], off
	v_lshl_add_u64 v[218:219], s[76:77], 0, v[130:131]
	s_mov_b32 m0, s75
	v_lshl_add_u64 v[220:221], s[54:55], 0, v[128:129]
	global_load_lds_dwordx4 v[218:219], off
	v_lshl_add_u64 v[218:219], s[76:77], 0, v[128:129]
	s_add_i32 m0, s75, 0x2000
	s_nop 0
	global_load_lds_dwordx4 v[218:219], off
	v_lshl_add_u64 v[218:219], s[54:55], 0, v[130:131]
	s_mov_b32 m0, s47
	s_nop 0
	global_load_lds_dwordx4 v[218:219], off
	s_mov_b32 m0, s60
	s_nop 0
	global_load_lds_dwordx4 v[220:221], off
	s_cmp_eq_u32 s98, 0
	s_cbranch_scc1 .Lpw8_4
	s_waitcnt vmcnt(24)
	s_branch .Lpwj_4

.LBB0_790:
	s_lshl_b32 s12, s12, 5
	s_mov_b64 s[16:17], 0x80
	s_and_b32 s36, s12, 0x60
	s_add_i32 m0, s63, 0x18000
	v_lshl_add_u64 v[6:7], v[6:7], 0, s[16:17]
	s_lshl_b32 s19, s13, 13
	s_lshl_b32 s12, s36, 7
	s_waitcnt vmcnt(2)
	s_barrier
	global_load_lds_dwordx4 v[6:7], off
	v_lshl_add_u64 v[4:5], v[4:5], 0, s[16:17]
	s_add_i32 m0, s63, 0x1a000
	s_add_i32 s68, s63, 0x8000
	s_add_i32 s69, s63, 0xa000
	global_load_lds_dwordx4 v[4:5], off
	v_lshl_add_u64 v[0:1], v[0:1], 0, s[16:17]
	s_mov_b32 m0, s68
	s_add_u32 s30, s54, 0xb0080
	global_load_lds_dwordx4 v[0:1], off
	v_lshl_add_u64 v[0:1], v[2:3], 0, s[16:17]
	s_mov_b32 m0, s69
	s_addc_u32 s31, s55, 0
	global_load_lds_dwordx4 v[0:1], off
	s_add_i32 m0, s63, 0x1c000
	v_lshl_add_u64 v[0:1], s[30:31], 0, v[130:131]
	global_load_lds_dwordx4 v[0:1], off
	v_lshl_add_u64 v[0:1], s[30:31], 0, v[134:135]
	s_add_i32 m0, s63, 0x1e000
	s_cmpk_lt_u32 s10, 0x100
	global_load_lds_dwordx4 v[0:1], off
	v_lshrrev_b32_e32 v1, 1, v8
	v_and_b32_e32 v1, 24, v1
	v_and_b32_e32 v0, 15, v8
	v_lshlrev_b32_e32 v2, 1, v1
	v_lshl_or_b32 v146, s13, 6, v0
	v_lshl_or_b32 v0, v0, 6, v2
	v_lshlrev_b32_e32 v2, 2, v8
	v_and_b32_e32 v2, 32, v2
	v_bitop3_b32 v3, v0, s19, v2 bitop3:0xde
	v_bitop3_b32 v147, v0, s12, v2 bitop3:0xde
	v_or_b32_e32 v148, s36, v1
	v_lshrrev_b32_e32 v1, 1, v9
	v_mul_lo_u32 v0, v11, s11
	s_mov_b32 s10, 0xb000
	v_mad_u64_u32 v[0:1], s[30:31], v1, s10, v[0:1]
	v_or_b32_e32 v0, v0, v10
	s_mov_b64 s[12:13], 0xb0080
	v_add_lshl_u32 v0, v0, v12, 1
	v_mov_b32_e32 v1, v131
	v_lshl_add_u64 v[136:137], v[0:1], 0, s[12:13]
	v_lshrrev_b32_e32 v1, 1, v13
	v_mul_lo_u32 v0, v14, s11
	v_mad_u64_u32 v[0:1], s[10:11], v1, s10, v[0:1]
	s_waitcnt vmcnt(6)
	v_or_b32_e32 v0, v0, v15
	s_sext_i32_i8 s83, s18
	s_cselect_b64 s[18:19], -1, 0
	v_add_lshl_u32 v0, v0, v16, 1
	v_mov_b32_e32 v1, v131
	s_add_i32 s70, 0, 0x10000
	s_add_i32 s71, 0, 0x14000
	v_lshl_add_u64 v[138:139], v[0:1], 0, s[12:13]
	v_mov_b64_e32 v[140:141], 0x200
	v_mov_b64_e32 v[142:143], 0x1ff
	v_add_u32_e32 v149, s70, v147
	v_add_u32_e32 v150, s71, v147
	v_add_u32_e32 v151, 0, v3
	s_mov_b64 s[30:31], 0x40000
	s_mov_b32 s72, 0x40000
	s_mov_b64 s[36:37], 0x48000
	s_mov_b32 s73, 0x48000
	s_mov_b64 s[44:45], 0x50000
	s_mov_b32 s74, 0x50000
	s_mov_b64 s[46:47], 0x58000
	s_mov_b32 s75, 0x58000
	s_barrier
	s_mov_b32 s98, 0
	s_branch .LBB0_793

.LBB0_792:
	s_andn2_b64 vcc, exec, s[10:11]
	s_mov_b32 s83, s76
	s_mov_b32 s82, s77
	s_mov_b64 s[54:55], s[48:49]
	s_mov_b64 s[52:53], s[12:13]
	s_mov_b32 s98, 1
	s_cbranch_vccz .LBB0_810

.LBB0_803:
	s_add_u32 s84, s54, 0x100
	s_addc_u32 s85, s55, 0
	s_mov_b32 s86, -2
	ds_read_b128 v[152:155], v149
	ds_read_b128 v[156:159], v149 offset:1024
	ds_read_b128 v[160:163], v149 offset:2048
	ds_read_b128 v[164:167], v149 offset:3072
	ds_read_b128 v[168:171], v150
	ds_read_b128 v[172:175], v150 offset:1024
	ds_read_b128 v[176:179], v150 offset:2048
	ds_read_b128 v[184:187], v150 offset:3072
	s_add_u32 s54, s52, 0x100
	s_addc_u32 s55, s53, 0
	s_cmp_eq_u32 s86, 40
	s_cselect_b32 s59, s13, s55
	s_cselect_b32 s58, s12, s54
	s_cselect_b32 s57, s49, s85
	s_cselect_b32 s56, s48, s84
	v_lshl_add_u64 v[144:145], s[52:53], 0, v[136:137]
	s_add_i32 m0, s63, 0xc000
	ds_read_b128 v[188:191], v151
	ds_read_b128 v[192:195], v151 offset:1024
	ds_read_b128 v[196:199], v151 offset:2048
	ds_read_b128 v[200:203], v151 offset:3072
	ds_read_b128 v[204:207], v151 offset:4096
	ds_read_b128 v[208:211], v151 offset:5120
	ds_read_b128 v[212:215], v151 offset:6144
	ds_read_b128 v[216:219], v151 offset:7168
	global_load_lds_dwordx4 v[144:145], off
	v_lshl_add_u64 v[144:145], s[52:53], 0, v[138:139]
	s_add_i32 m0, s63, 0xe000
	s_nop 0
	global_load_lds_dwordx4 v[144:145], off
	s_waitcnt vmcnt(24)
	s_waitcnt lgkmcnt(0)
	s_barrier
	s_setprio 1
	s_waitcnt lgkmcnt(0)
	v_mfma_f32_16x16x32_bf16 v[124:127], v[152:155], v[188:191], 0
	v_mfma_f32_16x16x32_bf16 v[120:123], v[160:163], v[188:191], 0
	v_mfma_f32_16x16x32_bf16 v[116:119], v[152:155], v[196:199], 0
	v_mfma_f32_16x16x32_bf16 v[108:111], v[160:163], v[196:199], 0
	v_mfma_f32_16x16x32_bf16 v[100:103], v[152:155], v[204:207], 0
	v_mfma_f32_16x16x32_bf16 v[92:95], v[160:163], v[204:207], 0
	v_mfma_f32_16x16x32_bf16 v[84:87], v[152:155], v[212:215], 0
	v_mfma_f32_16x16x32_bf16 v[76:79], v[160:163], v[212:215], 0
	v_mfma_f32_16x16x32_bf16 v[124:127], v[156:159], v[192:195], v[124:127]
	v_mfma_f32_16x16x32_bf16 v[120:123], v[164:167], v[192:195], v[120:123]
	v_mfma_f32_16x16x32_bf16 v[116:119], v[156:159], v[200:203], v[116:119]
	v_mfma_f32_16x16x32_bf16 v[108:111], v[164:167], v[200:203], v[108:111]
	v_mfma_f32_16x16x32_bf16 v[100:103], v[156:159], v[208:211], v[100:103]
	v_mfma_f32_16x16x32_bf16 v[92:95], v[164:167], v[208:211], v[92:95]
	v_mfma_f32_16x16x32_bf16 v[84:87], v[156:159], v[216:219], v[84:87]
	v_mfma_f32_16x16x32_bf16 v[76:79], v[164:167], v[216:219], v[76:79]
	s_setprio 0
	s_setprio 1
	v_mfma_f32_16x16x32_bf16 v[112:115], v[168:171], v[188:191], 0
	v_mfma_f32_16x16x32_bf16 v[104:107], v[176:179], v[188:191], 0
	v_mfma_f32_16x16x32_bf16 v[96:99], v[168:171], v[196:199], 0
	v_mfma_f32_16x16x32_bf16 v[88:91], v[176:179], v[196:199], 0
	v_mfma_f32_16x16x32_bf16 v[80:83], v[168:171], v[204:207], 0
	v_mfma_f32_16x16x32_bf16 v[72:75], v[176:179], v[204:207], 0
	v_mfma_f32_16x16x32_bf16 v[68:71], v[168:171], v[212:215], 0
	v_mfma_f32_16x16x32_bf16 v[64:67], v[176:179], v[212:215], 0
	v_mfma_f32_16x16x32_bf16 v[112:115], v[172:175], v[192:195], v[112:115]
	v_mfma_f32_16x16x32_bf16 v[104:107], v[184:187], v[192:195], v[104:107]
	v_mfma_f32_16x16x32_bf16 v[96:99], v[172:175], v[200:203], v[96:99]
	v_mfma_f32_16x16x32_bf16 v[88:91], v[184:187], v[200:203], v[88:91]
	v_mfma_f32_16x16x32_bf16 v[80:83], v[172:175], v[208:211], v[80:83]
	v_mfma_f32_16x16x32_bf16 v[72:75], v[184:187], v[208:211], v[72:75]
	v_mfma_f32_16x16x32_bf16 v[68:71], v[172:175], v[216:219], v[68:71]
	v_mfma_f32_16x16x32_bf16 v[64:67], v[184:187], v[216:219], v[64:67]
	s_setprio 0
	s_barrier
	s_add_i32 s52, s70, s62
	v_lshl_add_u64 v[144:145], s[56:57], 0, v[130:131]
	s_mov_b32 m0, s52
	ds_read_b128 v[188:191], v151 offset:16384
	ds_read_b128 v[192:195], v151 offset:17408
	ds_read_b128 v[196:199], v151 offset:18432
	ds_read_b128 v[200:203], v151 offset:19456
	ds_read_b128 v[204:207], v151 offset:20480
	ds_read_b128 v[208:211], v151 offset:21504
	ds_read_b128 v[212:215], v151 offset:22528
	ds_read_b128 v[216:219], v151 offset:23552
	global_load_lds_dwordx4 v[144:145], off
	s_add_i32 m0, s52, 0x2000
	s_add_u32 s52, s56, 0xb0000
	v_lshl_add_u64 v[220:221], s[56:57], 0, v[134:135]
	s_addc_u32 s53, s57, 0
	s_add_i32 s79, s71, s62
	global_load_lds_dwordx4 v[220:221], off
	v_lshl_add_u64 v[222:223], s[52:53], 0, v[130:131]
	s_mov_b32 m0, s79
	v_lshl_add_u64 v[224:225], s[58:59], 0, v[132:133]
	global_load_lds_dwordx4 v[222:223], off
	v_lshl_add_u64 v[222:223], s[52:53], 0, v[134:135]
	s_add_i32 m0, s79, 0x2000
	s_nop 0
	global_load_lds_dwordx4 v[222:223], off
	v_lshl_add_u64 v[222:223], s[58:59], 0, v[128:129]
	s_mov_b32 m0, s63
	s_nop 0
	global_load_lds_dwordx4 v[222:223], off
	s_mov_b32 m0, s64
	s_nop 0
	global_load_lds_dwordx4 v[224:225], off
	s_cmp_eq_u32 s98, 0
	s_cbranch_scc1 .Lpw8_5
	s_waitcnt vmcnt(24)
	s_branch .Lpwj_5

.LBB0_925:
	s_lshl_b32 s36, s12, 5
	s_mov_b64 s[12:13], 0x80
	s_and_b32 s74, s36, 0x60
	s_add_i32 m0, s69, 0x18000
	v_lshl_add_u64 v[6:7], v[6:7], 0, s[12:13]
	s_lshl_b32 s17, s16, 13
	s_lshl_b32 s37, s74, 7
	s_waitcnt vmcnt(2)
	s_barrier
	global_load_lds_dwordx4 v[6:7], off
	v_lshl_add_u64 v[4:5], v[4:5], 0, s[12:13]
	s_add_i32 m0, s69, 0x1a000
	s_add_i32 s75, s69, 0x8000
	s_add_i32 s76, s69, 0xa000
	global_load_lds_dwordx4 v[4:5], off
	v_lshl_add_u64 v[0:1], v[0:1], 0, s[12:13]
	s_mov_b32 m0, s75
	s_add_u32 s18, s62, 0x40080
	global_load_lds_dwordx4 v[0:1], off
	v_lshl_add_u64 v[0:1], v[2:3], 0, s[12:13]
	s_mov_b32 m0, s76
	s_addc_u32 s19, s63, 0
	global_load_lds_dwordx4 v[0:1], off
	s_add_i32 m0, s69, 0x1c000
	v_lshl_add_u64 v[0:1], s[18:19], 0, v[130:131]
	global_load_lds_dwordx4 v[0:1], off
	v_lshl_add_u64 v[0:1], s[18:19], 0, v[134:135]
	s_add_i32 m0, s69, 0x1e000
	s_cmpk_lt_u32 s11, 0x100
	global_load_lds_dwordx4 v[0:1], off
	v_lshrrev_b32_e32 v1, 1, v8
	v_and_b32_e32 v1, 24, v1
	v_and_b32_e32 v0, 15, v8
	v_lshlrev_b32_e32 v2, 1, v1
	v_lshl_or_b32 v146, s16, 6, v0
	v_lshl_or_b32 v0, v0, 6, v2
	v_lshlrev_b32_e32 v2, 2, v8
	v_and_b32_e32 v2, 32, v2
	v_bitop3_b32 v3, v0, s17, v2 bitop3:0xde
	v_bitop3_b32 v147, v0, s37, v2 bitop3:0xde
	v_and_or_b32 v0, s36, 32, v1
	v_lshlrev_b32_e32 v0, 1, v0
	v_mov_b32_e32 v1, v131
	v_lshl_add_u64 v[136:137], s[30:31], 0, v[0:1]
	v_lshlrev_b32_e32 v0, 14, v9
	v_and_b32_e32 v0, 0xffff8000, v0
	v_lshl_add_u32 v0, v10, 11, v0
	v_and_b32_e32 v1, 1, v9
	v_lshl_or_b32 v0, v1, 6, v0
	v_lshl_add_u32 v138, v11, 1, v0
	v_lshlrev_b32_e32 v0, 14, v12
	v_and_b32_e32 v0, 0xffff8000, v0
	s_waitcnt vmcnt(6)
	v_lshl_add_u32 v0, v13, 11, v0
	v_and_b32_e32 v1, 1, v12
	s_cselect_b64 s[16:17], -1, 0
	v_lshl_or_b32 v0, v1, 6, v0
	s_add_i32 s77, 0, 0x10000
	s_add_i32 s82, 0, 0x14000
	s_sext_i32_i8 s59, s10
	v_mov_b32_e32 v139, v131
	v_lshl_add_u32 v140, v14, 1, v0
	v_mov_b32_e32 v141, v131
	v_mov_b64_e32 v[142:143], 0x100
	v_mov_b64_e32 v[144:145], 0xff
	v_add_u32_e32 v148, s77, v147
	v_add_u32_e32 v149, s82, v147
	v_add_u32_e32 v150, 0, v3
	s_mov_b64 s[18:19], 0x4000
	s_mov_b64 s[36:37], 0x4800
	s_mov_b64 s[44:45], 0x5000
	s_mov_b64 s[46:47], 0x5800
	s_barrier
	s_mov_b32 s98, 0
	s_branch .LBB0_928

.LBB0_927:
	s_andn2_b64 vcc, exec, s[10:11]
	s_mov_b32 s59, s48
	s_mov_b32 s58, s52
	s_mov_b64 s[62:63], s[56:57]
	s_mov_b64 s[60:61], s[54:55]
	s_mov_b32 s98, 1
	s_cbranch_vccz .LBB0_941

.LBB0_934:
	s_ashr_i32 s53, s52, 31
	s_lshl_b64 s[54:55], s[52:53], 19
	s_add_u32 s54, s80, s54
	s_addc_u32 s55, s81, s55
	s_and_b64 s[56:57], s[10:11], exec
	s_cselect_b32 s53, s55, s61
	s_cselect_b32 s83, s54, s60
	s_ashr_i32 s49, s48, 31
	s_lshl_b64 s[56:57], s[48:49], 19
	s_add_u32 s56, s66, s56
	s_addc_u32 s57, s67, s57
	s_and_b64 s[64:65], s[10:11], exec
	s_cselect_b32 s49, s57, s63
	s_cselect_b32 s84, s56, s62
	s_add_u32 s60, s60, 0x40080
	s_addc_u32 s61, s61, 0
	s_add_u32 s85, s62, 0x100
	s_addc_u32 s86, s63, 0
	s_mov_b32 s87, -2
	ds_read_b128 v[152:155], v148
	ds_read_b128 v[156:159], v148 offset:1024
	ds_read_b128 v[160:163], v148 offset:2048
	ds_read_b128 v[164:167], v148 offset:3072
	ds_read_b128 v[168:171], v149
	ds_read_b128 v[172:175], v149 offset:1024
	ds_read_b128 v[176:179], v149 offset:2048
	ds_read_b128 v[184:187], v149 offset:3072
	s_add_u32 s62, s60, 0xfffc0080
	s_addc_u32 s63, s61, -1
	s_cmp_eq_u32 s87, 12
	s_cselect_b32 s65, s53, s63
	s_cselect_b32 s64, s83, s62
	s_cselect_b32 s63, s49, s86
	s_cselect_b32 s62, s84, s85
	v_lshl_add_u64 v[220:221], s[60:61], 0, v[138:139]
	s_add_i32 m0, s69, 0xc000
	ds_read_b128 v[188:191], v150
	ds_read_b128 v[192:195], v150 offset:1024
	ds_read_b128 v[196:199], v150 offset:2048
	ds_read_b128 v[200:203], v150 offset:3072
	ds_read_b128 v[204:207], v150 offset:4096
	ds_read_b128 v[208:211], v150 offset:5120
	ds_read_b128 v[212:215], v150 offset:6144
	ds_read_b128 v[216:219], v150 offset:7168
	global_load_lds_dwordx4 v[220:221], off
	v_lshl_add_u64 v[220:221], s[60:61], 0, v[140:141]
	s_add_i32 m0, s69, 0xe000
	s_nop 0
	global_load_lds_dwordx4 v[220:221], off
	s_waitcnt vmcnt(24)
	s_waitcnt lgkmcnt(0)
	s_barrier
	s_setprio 1
	s_waitcnt lgkmcnt(0)
	v_mfma_f32_16x16x32_bf16 v[124:127], v[152:155], v[188:191], 0
	v_mfma_f32_16x16x32_bf16 v[120:123], v[160:163], v[188:191], 0
	v_mfma_f32_16x16x32_bf16 v[116:119], v[152:155], v[196:199], 0
	v_mfma_f32_16x16x32_bf16 v[112:115], v[160:163], v[196:199], 0
	v_mfma_f32_16x16x32_bf16 v[108:111], v[152:155], v[204:207], 0
	v_mfma_f32_16x16x32_bf16 v[104:107], v[160:163], v[204:207], 0
	v_mfma_f32_16x16x32_bf16 v[100:103], v[152:155], v[212:215], 0
	v_mfma_f32_16x16x32_bf16 v[96:99], v[160:163], v[212:215], 0
	v_mfma_f32_16x16x32_bf16 v[124:127], v[156:159], v[192:195], v[124:127]
	v_mfma_f32_16x16x32_bf16 v[120:123], v[164:167], v[192:195], v[120:123]
	v_mfma_f32_16x16x32_bf16 v[116:119], v[156:159], v[200:203], v[116:119]
	v_mfma_f32_16x16x32_bf16 v[112:115], v[164:167], v[200:203], v[112:115]
	v_mfma_f32_16x16x32_bf16 v[108:111], v[156:159], v[208:211], v[108:111]
	v_mfma_f32_16x16x32_bf16 v[104:107], v[164:167], v[208:211], v[104:107]
	v_mfma_f32_16x16x32_bf16 v[100:103], v[156:159], v[216:219], v[100:103]
	v_mfma_f32_16x16x32_bf16 v[96:99], v[164:167], v[216:219], v[96:99]
	s_setprio 0
	s_setprio 1
	v_mfma_f32_16x16x32_bf16 v[76:79], v[168:171], v[188:191], 0
	v_mfma_f32_16x16x32_bf16 v[68:71], v[176:179], v[188:191], 0
	v_mfma_f32_16x16x32_bf16 v[60:63], v[168:171], v[196:199], 0
	v_mfma_f32_16x16x32_bf16 v[52:55], v[176:179], v[196:199], 0
	v_mfma_f32_16x16x32_bf16 v[44:47], v[168:171], v[204:207], 0
	v_mfma_f32_16x16x32_bf16 v[40:43], v[176:179], v[204:207], 0
	v_mfma_f32_16x16x32_bf16 v[36:39], v[168:171], v[212:215], 0
	v_mfma_f32_16x16x32_bf16 v[32:35], v[176:179], v[212:215], 0
	v_mfma_f32_16x16x32_bf16 v[76:79], v[172:175], v[192:195], v[76:79]
	v_mfma_f32_16x16x32_bf16 v[68:71], v[184:187], v[192:195], v[68:71]
	v_mfma_f32_16x16x32_bf16 v[60:63], v[172:175], v[200:203], v[60:63]
	v_mfma_f32_16x16x32_bf16 v[52:55], v[184:187], v[200:203], v[52:55]
	v_mfma_f32_16x16x32_bf16 v[44:47], v[172:175], v[208:211], v[44:47]
	v_mfma_f32_16x16x32_bf16 v[40:43], v[184:187], v[208:211], v[40:43]
	v_mfma_f32_16x16x32_bf16 v[36:39], v[172:175], v[216:219], v[36:39]
	v_mfma_f32_16x16x32_bf16 v[32:35], v[184:187], v[216:219], v[32:35]
	s_setprio 0
	s_barrier
	s_add_i32 s79, s77, s68
	v_lshl_add_u64 v[220:221], s[62:63], 0, v[130:131]
	s_mov_b32 m0, s79
	ds_read_b128 v[188:191], v150 offset:16384
	ds_read_b128 v[192:195], v150 offset:17408
	ds_read_b128 v[196:199], v150 offset:18432
	ds_read_b128 v[200:203], v150 offset:19456
	ds_read_b128 v[204:207], v150 offset:20480
	ds_read_b128 v[208:211], v150 offset:21504
	ds_read_b128 v[212:215], v150 offset:22528
	ds_read_b128 v[216:219], v150 offset:23552
	global_load_lds_dwordx4 v[220:221], off
	s_add_i32 m0, s79, 0x2000
	s_add_u32 s88, s62, 0x40000
	v_lshl_add_u64 v[222:223], s[62:63], 0, v[134:135]
	s_addc_u32 s89, s63, 0
	s_add_i32 s79, s82, s68
	global_load_lds_dwordx4 v[222:223], off
	v_lshl_add_u64 v[224:225], s[88:89], 0, v[130:131]
	s_mov_b32 m0, s79
	v_lshl_add_u64 v[226:227], s[64:65], 0, v[132:133]
	global_load_lds_dwordx4 v[224:225], off
	v_lshl_add_u64 v[224:225], s[88:89], 0, v[134:135]
	s_add_i32 m0, s79, 0x2000
	s_nop 0
	global_load_lds_dwordx4 v[224:225], off
	v_lshl_add_u64 v[224:225], s[64:65], 0, v[128:129]
	s_mov_b32 m0, s69
	s_nop 0
	global_load_lds_dwordx4 v[224:225], off
	s_mov_b32 m0, s70
	s_nop 0
	global_load_lds_dwordx4 v[226:227], off
	s_cmp_eq_u32 s98, 0
	s_cbranch_scc1 .Lpw8_6
	s_waitcnt vmcnt(24)
	s_branch .Lpwj_6

.Lpwj_6:
	s_waitcnt lgkmcnt(0)
	s_barrier
	s_setprio 1
	s_waitcnt lgkmcnt(0)
	v_mfma_f32_16x16x32_bf16 v[92:95], v[152:155], v[188:191], 0
	v_mfma_f32_16x16x32_bf16 v[88:91], v[160:163], v[188:191], 0
	v_mfma_f32_16x16x32_bf16 v[84:87], v[152:155], v[196:199], 0
	v_mfma_f32_16x16x32_bf16 v[80:83], v[160:163], v[196:199], 0
	v_mfma_f32_16x16x32_bf16 v[72:75], v[152:155], v[204:207], 0
	v_mfma_f32_16x16x32_bf16 v[64:67], v[160:163], v[204:207], 0
	v_mfma_f32_16x16x32_bf16 v[56:59], v[152:155], v[212:215], 0
	v_mfma_f32_16x16x32_bf16 v[48:51], v[160:163], v[212:215], 0
	v_mfma_f32_16x16x32_bf16 v[92:95], v[156:159], v[192:195], v[92:95]
	v_mfma_f32_16x16x32_bf16 v[88:91], v[164:167], v[192:195], v[88:91]
	v_mfma_f32_16x16x32_bf16 v[84:87], v[156:159], v[200:203], v[84:87]
	v_mfma_f32_16x16x32_bf16 v[80:83], v[164:167], v[200:203], v[80:83]
	v_mfma_f32_16x16x32_bf16 v[72:75], v[156:159], v[208:211], v[72:75]
	v_mfma_f32_16x16x32_bf16 v[64:67], v[164:167], v[208:211], v[64:67]
	v_mfma_f32_16x16x32_bf16 v[56:59], v[156:159], v[216:219], v[56:59]
	v_mfma_f32_16x16x32_bf16 v[48:51], v[164:167], v[216:219], v[48:51]
	s_setprio 0
	s_setprio 1
	v_mfma_f32_16x16x32_bf16 v[28:31], v[168:171], v[188:191], 0
	v_mfma_f32_16x16x32_bf16 v[24:27], v[176:179], v[188:191], 0
	v_mfma_f32_16x16x32_bf16 v[20:23], v[168:171], v[196:199], 0
	v_mfma_f32_16x16x32_bf16 v[16:19], v[176:179], v[196:199], 0
	v_mfma_f32_16x16x32_bf16 v[12:15], v[168:171], v[204:207], 0
	v_mfma_f32_16x16x32_bf16 v[8:11], v[176:179], v[204:207], 0
	v_mfma_f32_16x16x32_bf16 v[4:7], v[168:171], v[212:215], 0
	v_mfma_f32_16x16x32_bf16 v[0:3], v[176:179], v[212:215], 0
	v_mfma_f32_16x16x32_bf16 v[28:31], v[172:175], v[192:195], v[28:31]
	v_mfma_f32_16x16x32_bf16 v[24:27], v[184:187], v[192:195], v[24:27]
	v_mfma_f32_16x16x32_bf16 v[20:23], v[172:175], v[200:203], v[20:23]
	v_mfma_f32_16x16x32_bf16 v[16:19], v[184:187], v[200:203], v[16:19]
	v_mfma_f32_16x16x32_bf16 v[12:15], v[172:175], v[208:211], v[12:15]
	v_mfma_f32_16x16x32_bf16 v[8:11], v[184:187], v[208:211], v[8:11]
	v_mfma_f32_16x16x32_bf16 v[4:7], v[172:175], v[216:219], v[4:7]
	v_mfma_f32_16x16x32_bf16 v[0:3], v[184:187], v[216:219], v[0:3]
	s_setprio 0
	s_barrier
	s_branch .Lmid_gemm6

.LBB0_945:
	s_and_b32 s36, s12, 3
	s_mov_b64 s[12:13], 0x80
	s_add_i32 m0, s49, 0x18000
	v_lshl_add_u64 v[6:7], v[6:7], 0, s[12:13]
	s_lshl_b32 s17, s16, 13
	s_lshl_b32 s37, s36, 12
	s_waitcnt vmcnt(2)
	s_barrier
	global_load_lds_dwordx4 v[6:7], off
	v_lshl_add_u64 v[4:5], v[4:5], 0, s[12:13]
	s_add_i32 m0, s49, 0x1a000
	s_add_i32 s66, s49, 0x8000
	s_add_i32 s67, s49, 0xa000
	global_load_lds_dwordx4 v[4:5], off
	v_lshl_add_u64 v[0:1], v[0:1], 0, s[12:13]
	s_mov_b32 m0, s66
	s_add_u32 s18, s54, 0x40080
	global_load_lds_dwordx4 v[0:1], off
	v_lshl_add_u64 v[0:1], v[2:3], 0, s[12:13]
	s_mov_b32 m0, s67
	s_addc_u32 s19, s55, 0
	global_load_lds_dwordx4 v[0:1], off
	s_add_i32 m0, s49, 0x1c000
	v_lshl_add_u64 v[0:1], s[18:19], 0, v[130:131]
	global_load_lds_dwordx4 v[0:1], off
	v_lshl_add_u64 v[0:1], s[18:19], 0, v[128:129]
	s_add_i32 m0, s49, 0x1e000
	s_cmpk_lt_u32 s11, 0x100
	global_load_lds_dwordx4 v[0:1], off
	v_bfe_u32 v1, v9, 4, 2
	v_and_b32_e32 v0, 15, v9
	v_lshlrev_b32_e32 v2, 4, v1
	v_lshl_or_b32 v144, s16, 6, v0
	v_lshl_or_b32 v0, v0, 6, v2
	v_lshlrev_b32_e32 v2, 2, v9
	v_and_b32_e32 v2, 32, v2
	v_bitop3_b32 v3, v0, s17, v2 bitop3:0xde
	v_bitop3_b32 v145, v0, s37, v2 bitop3:0xde
	v_lshlrev_b32_e32 v0, 2, v1
	v_lshl_or_b32 v146, s36, 4, v0
	v_lshlrev_b32_e32 v0, 14, v12
	v_and_b32_e32 v0, 0xffff8000, v0
	v_lshl_add_u32 v0, v13, 11, v0
	v_and_b32_e32 v1, 1, v12
	v_lshl_or_b32 v0, v1, 6, v0
	v_lshl_add_u32 v132, v14, 1, v0
	v_lshlrev_b32_e32 v0, 14, v8
	v_and_b32_e32 v0, 0xffff8000, v0
	s_waitcnt vmcnt(6)
	v_lshl_add_u32 v0, v10, 11, v0
	v_and_b32_e32 v1, 1, v8
	s_cselect_b64 s[16:17], -1, 0
	v_lshl_or_b32 v0, v1, 6, v0
	s_add_i32 s68, 0, 0x10000
	s_add_i32 s69, 0, 0x14000
	s_sext_i32_i16 s71, s10
	v_mov_b32_e32 v133, v131
	v_lshl_add_u32 v134, v11, 1, v0
	v_mov_b32_e32 v135, v131
	v_mov_b64_e32 v[136:137], 0xb00
	v_mov_b64_e32 v[138:139], 0xaff
	v_add_u32_e32 v147, s68, v145
	v_add_u32_e32 v148, s69, v145
	v_add_u32_e32 v149, 0, v3
	s_movk_i32 s70, 0x1600
	s_barrier
	s_mov_b32 s98, 0
	s_branch .LBB0_948

.LBB0_947:
	s_andn2_b64 vcc, exec, s[10:11]
	s_mov_b32 s71, s18
	s_mov_b32 s48, s36
	s_mov_b64 s[54:55], s[46:47]
	s_mov_b64 s[52:53], s[44:45]
	s_mov_b32 s98, 1
	s_cbranch_vccz .LBB0_957

.LBB0_950:
	s_ashr_i32 s37, s36, 31
	s_lshl_b64 s[44:45], s[36:37], 19
	s_add_u32 s44, s80, s44
	s_addc_u32 s45, s81, s45
	s_and_b64 s[46:47], s[10:11], exec
	s_cselect_b32 s37, s45, s53
	s_cselect_b32 s72, s44, s52
	s_ashr_i32 s19, s18, 31
	s_lshl_b64 s[46:47], s[18:19], 19
	s_add_u32 s46, s58, s46
	s_addc_u32 s47, s59, s47
	s_and_b64 s[56:57], s[10:11], exec
	s_cselect_b32 s19, s47, s55
	s_cselect_b32 s73, s46, s54
	s_add_u32 s52, s52, 0x40080
	s_addc_u32 s53, s53, 0
	s_add_u32 s74, s54, 0x100
	s_addc_u32 s75, s55, 0
	s_mov_b32 s76, -2
	ds_read_b128 v[140:143], v147
	ds_read_b128 v[150:153], v147 offset:1024
	ds_read_b128 v[154:157], v147 offset:2048
	ds_read_b128 v[158:161], v147 offset:3072
	ds_read_b128 v[162:165], v148
	ds_read_b128 v[166:169], v148 offset:1024
	ds_read_b128 v[170:173], v148 offset:2048
	ds_read_b128 v[174:177], v148 offset:3072
	s_add_u32 s54, s52, 0xfffc0080
	s_addc_u32 s55, s53, -1
	s_cmp_eq_u32 s76, 12
	s_cselect_b32 s57, s37, s55
	s_cselect_b32 s56, s72, s54
	s_cselect_b32 s55, s19, s75
	s_cselect_b32 s54, s73, s74
	v_lshl_add_u64 v[178:179], s[52:53], 0, v[132:133]
	s_add_i32 m0, s49, 0xc000
	ds_read_b128 v[184:187], v149
	ds_read_b128 v[188:191], v149 offset:1024
	ds_read_b128 v[192:195], v149 offset:2048
	ds_read_b128 v[196:199], v149 offset:3072
	ds_read_b128 v[200:203], v149 offset:4096
	ds_read_b128 v[204:207], v149 offset:5120
	ds_read_b128 v[208:211], v149 offset:6144
	ds_read_b128 v[212:215], v149 offset:7168
	global_load_lds_dwordx4 v[178:179], off
	v_lshl_add_u64 v[178:179], s[52:53], 0, v[134:135]
	s_add_i32 m0, s49, 0xe000
	s_nop 0
	global_load_lds_dwordx4 v[178:179], off
	s_waitcnt vmcnt(24)
	s_waitcnt lgkmcnt(0)
	s_barrier
	s_setprio 1
	s_waitcnt lgkmcnt(0)
	v_mfma_f32_16x16x32_bf16 v[124:127], v[140:143], v[184:187], 0
	v_mfma_f32_16x16x32_bf16 v[120:123], v[154:157], v[184:187], 0
	v_mfma_f32_16x16x32_bf16 v[108:111], v[140:143], v[192:195], 0
	v_mfma_f32_16x16x32_bf16 v[104:107], v[154:157], v[192:195], 0
	v_mfma_f32_16x16x32_bf16 v[92:95], v[140:143], v[200:203], 0
	v_mfma_f32_16x16x32_bf16 v[88:91], v[154:157], v[200:203], 0
	v_mfma_f32_16x16x32_bf16 v[76:79], v[140:143], v[208:211], 0
	v_mfma_f32_16x16x32_bf16 v[72:75], v[154:157], v[208:211], 0
	v_mfma_f32_16x16x32_bf16 v[124:127], v[150:153], v[188:191], v[124:127]
	v_mfma_f32_16x16x32_bf16 v[120:123], v[158:161], v[188:191], v[120:123]
	v_mfma_f32_16x16x32_bf16 v[108:111], v[150:153], v[196:199], v[108:111]
	v_mfma_f32_16x16x32_bf16 v[104:107], v[158:161], v[196:199], v[104:107]
	v_mfma_f32_16x16x32_bf16 v[92:95], v[150:153], v[204:207], v[92:95]
	v_mfma_f32_16x16x32_bf16 v[88:91], v[158:161], v[204:207], v[88:91]
	v_mfma_f32_16x16x32_bf16 v[76:79], v[150:153], v[212:215], v[76:79]
	v_mfma_f32_16x16x32_bf16 v[72:75], v[158:161], v[212:215], v[72:75]
	s_setprio 0
	s_setprio 1
	v_mfma_f32_16x16x32_bf16 v[116:119], v[162:165], v[184:187], 0
	v_mfma_f32_16x16x32_bf16 v[112:115], v[170:173], v[184:187], 0
	v_mfma_f32_16x16x32_bf16 v[100:103], v[162:165], v[192:195], 0
	v_mfma_f32_16x16x32_bf16 v[96:99], v[170:173], v[192:195], 0
	v_mfma_f32_16x16x32_bf16 v[84:87], v[162:165], v[200:203], 0
	v_mfma_f32_16x16x32_bf16 v[80:83], v[170:173], v[200:203], 0
	v_mfma_f32_16x16x32_bf16 v[68:71], v[162:165], v[208:211], 0
	v_mfma_f32_16x16x32_bf16 v[64:67], v[170:173], v[208:211], 0
	v_mfma_f32_16x16x32_bf16 v[116:119], v[166:169], v[188:191], v[116:119]
	v_mfma_f32_16x16x32_bf16 v[112:115], v[174:177], v[188:191], v[112:115]
	v_mfma_f32_16x16x32_bf16 v[100:103], v[166:169], v[196:199], v[100:103]
	v_mfma_f32_16x16x32_bf16 v[96:99], v[174:177], v[196:199], v[96:99]
	v_mfma_f32_16x16x32_bf16 v[84:87], v[166:169], v[204:207], v[84:87]
	v_mfma_f32_16x16x32_bf16 v[80:83], v[174:177], v[204:207], v[80:83]
	v_mfma_f32_16x16x32_bf16 v[68:71], v[166:169], v[212:215], v[68:71]
	v_mfma_f32_16x16x32_bf16 v[64:67], v[174:177], v[212:215], v[64:67]
	s_setprio 0
	s_barrier
	s_add_i32 s77, s68, s60
	v_lshl_add_u64 v[178:179], s[54:55], 0, v[130:131]
	s_mov_b32 m0, s77
	ds_read_b128 v[184:187], v149 offset:16384
	ds_read_b128 v[188:191], v149 offset:17408
	ds_read_b128 v[192:195], v149 offset:18432
	ds_read_b128 v[196:199], v149 offset:19456
	ds_read_b128 v[200:203], v149 offset:20480
	ds_read_b128 v[204:207], v149 offset:21504
	ds_read_b128 v[208:211], v149 offset:22528
	ds_read_b128 v[212:215], v149 offset:23552
	global_load_lds_dwordx4 v[178:179], off
	s_add_i32 m0, s77, 0x2000
	s_add_u32 s82, s54, 0x40000
	v_lshl_add_u64 v[216:217], s[54:55], 0, v[128:129]
	s_addc_u32 s83, s55, 0
	s_add_i32 s77, s69, s60
	global_load_lds_dwordx4 v[216:217], off
	v_lshl_add_u64 v[218:219], s[82:83], 0, v[130:131]
	s_mov_b32 m0, s77
	v_lshl_add_u64 v[220:221], s[56:57], 0, v[128:129]
	global_load_lds_dwordx4 v[218:219], off
	v_lshl_add_u64 v[218:219], s[82:83], 0, v[128:129]
	s_add_i32 m0, s77, 0x2000
	s_nop 0
	global_load_lds_dwordx4 v[218:219], off
	v_lshl_add_u64 v[218:219], s[56:57], 0, v[130:131]
	s_mov_b32 m0, s49
	s_nop 0
	global_load_lds_dwordx4 v[218:219], off
	s_mov_b32 m0, s62
	s_nop 0
	global_load_lds_dwordx4 v[220:221], off
	s_cmp_eq_u32 s98, 0
	s_cbranch_scc1 .Lpw8_7
	s_waitcnt vmcnt(24)
	s_branch .Lpwj_7

.LBB0_1017:
	s_lshl_b32 s12, s12, 5
	s_mov_b64 s[16:17], 0x80
	s_and_b32 s44, s12, 0x60
	s_add_i32 m0, s65, 0x18000
	v_lshl_add_u64 v[6:7], v[6:7], 0, s[16:17]
	s_lshl_b32 s19, s13, 13
	s_lshl_b32 s12, s44, 7
	s_waitcnt vmcnt(2)
	s_barrier
	global_load_lds_dwordx4 v[6:7], off
	v_lshl_add_u64 v[4:5], v[4:5], 0, s[16:17]
	s_add_i32 m0, s65, 0x1a000
	s_add_i32 s70, s65, 0x8000
	s_add_i32 s71, s65, 0xa000
	global_load_lds_dwordx4 v[4:5], off
	v_lshl_add_u64 v[0:1], v[0:1], 0, s[16:17]
	s_mov_b32 m0, s70
	s_add_u32 s36, s56, 0xb0080
	global_load_lds_dwordx4 v[0:1], off
	v_lshl_add_u64 v[0:1], v[2:3], 0, s[16:17]
	s_mov_b32 m0, s71
	s_addc_u32 s37, s57, 0
	global_load_lds_dwordx4 v[0:1], off
	s_add_i32 m0, s65, 0x1c000
	v_lshl_add_u64 v[0:1], s[36:37], 0, v[130:131]
	global_load_lds_dwordx4 v[0:1], off
	v_lshl_add_u64 v[0:1], s[36:37], 0, v[134:135]
	s_add_i32 m0, s65, 0x1e000
	s_cmpk_lt_u32 s10, 0x100
	global_load_lds_dwordx4 v[0:1], off
	v_lshrrev_b32_e32 v1, 1, v8
	v_and_b32_e32 v1, 24, v1
	v_and_b32_e32 v0, 15, v8
	v_lshlrev_b32_e32 v2, 1, v1
	v_lshl_or_b32 v146, s13, 6, v0
	v_lshl_or_b32 v0, v0, 6, v2
	v_lshlrev_b32_e32 v2, 2, v8
	v_and_b32_e32 v2, 32, v2
	v_bitop3_b32 v3, v0, s19, v2 bitop3:0xde
	v_bitop3_b32 v147, v0, s12, v2 bitop3:0xde
	v_or_b32_e32 v148, s44, v1
	v_lshrrev_b32_e32 v1, 1, v9
	v_mul_lo_u32 v0, v11, s11
	s_mov_b32 s10, 0xb000
	v_mad_u64_u32 v[0:1], s[36:37], v1, s10, v[0:1]
	v_or_b32_e32 v0, v0, v10
	s_mov_b64 s[12:13], 0xb0080
	v_add_lshl_u32 v0, v0, v12, 1
	v_mov_b32_e32 v1, v131
	v_lshl_add_u64 v[136:137], v[0:1], 0, s[12:13]
	v_lshrrev_b32_e32 v1, 1, v13
	v_mul_lo_u32 v0, v14, s11
	v_mad_u64_u32 v[0:1], s[10:11], v1, s10, v[0:1]
	s_waitcnt vmcnt(6)
	v_or_b32_e32 v0, v0, v15
	s_sext_i32_i8 s85, s18
	s_cselect_b64 s[18:19], -1, 0
	v_add_lshl_u32 v0, v0, v16, 1
	v_mov_b32_e32 v1, v131
	s_add_i32 s72, 0, 0x10000
	s_add_i32 s73, 0, 0x14000
	v_lshl_add_u64 v[138:139], v[0:1], 0, s[12:13]
	v_mov_b64_e32 v[140:141], 0x200
	v_mov_b64_e32 v[142:143], 0x1ff
	v_add_u32_e32 v149, s72, v147
	v_add_u32_e32 v150, s73, v147
	v_add_u32_e32 v151, 0, v3
	s_mov_b64 s[36:37], 0x40000
	s_mov_b32 s74, 0x40000
	s_mov_b64 s[44:45], 0x48000
	s_mov_b32 s75, 0x48000
	s_mov_b64 s[46:47], 0x50000
	s_mov_b32 s76, 0x50000
	s_mov_b64 s[48:49], 0x58000
	s_mov_b32 s77, 0x58000
	s_barrier
	s_mov_b32 s98, 0
	s_branch .LBB0_1020

.LBB0_1019:
	s_andn2_b64 vcc, exec, s[10:11]
	s_mov_b32 s85, s82
	s_mov_b32 s84, s83
	s_mov_b64 s[56:57], s[52:53]
	s_mov_b64 s[54:55], s[12:13]
	s_mov_b32 s98, 1
	s_cbranch_vccz .LBB0_1037

.LBB0_1030:
	s_add_u32 s86, s56, 0x100
	s_addc_u32 s87, s57, 0
	s_mov_b32 s88, -2
	ds_read_b128 v[152:155], v149
	ds_read_b128 v[156:159], v149 offset:1024
	ds_read_b128 v[160:163], v149 offset:2048
	ds_read_b128 v[164:167], v149 offset:3072
	ds_read_b128 v[168:171], v150
	ds_read_b128 v[172:175], v150 offset:1024
	ds_read_b128 v[176:179], v150 offset:2048
	ds_read_b128 v[184:187], v150 offset:3072
	s_add_u32 s56, s54, 0x100
	s_addc_u32 s57, s55, 0
	s_cmp_eq_u32 s88, 40
	s_cselect_b32 s61, s13, s57
	s_cselect_b32 s60, s12, s56
	s_cselect_b32 s59, s53, s87
	s_cselect_b32 s58, s52, s86
	v_lshl_add_u64 v[144:145], s[54:55], 0, v[136:137]
	s_add_i32 m0, s65, 0xc000
	ds_read_b128 v[188:191], v151
	ds_read_b128 v[192:195], v151 offset:1024
	ds_read_b128 v[196:199], v151 offset:2048
	ds_read_b128 v[200:203], v151 offset:3072
	ds_read_b128 v[204:207], v151 offset:4096
	ds_read_b128 v[208:211], v151 offset:5120
	ds_read_b128 v[212:215], v151 offset:6144
	ds_read_b128 v[216:219], v151 offset:7168
	global_load_lds_dwordx4 v[144:145], off
	v_lshl_add_u64 v[144:145], s[54:55], 0, v[138:139]
	s_add_i32 m0, s65, 0xe000
	s_nop 0
	global_load_lds_dwordx4 v[144:145], off
	s_waitcnt vmcnt(24)
	s_waitcnt lgkmcnt(0)
	s_barrier
	s_setprio 1
	s_waitcnt lgkmcnt(0)
	v_mfma_f32_16x16x32_bf16 v[124:127], v[152:155], v[188:191], 0
	v_mfma_f32_16x16x32_bf16 v[120:123], v[160:163], v[188:191], 0
	v_mfma_f32_16x16x32_bf16 v[116:119], v[152:155], v[196:199], 0
	v_mfma_f32_16x16x32_bf16 v[108:111], v[160:163], v[196:199], 0
	v_mfma_f32_16x16x32_bf16 v[100:103], v[152:155], v[204:207], 0
	v_mfma_f32_16x16x32_bf16 v[92:95], v[160:163], v[204:207], 0
	v_mfma_f32_16x16x32_bf16 v[84:87], v[152:155], v[212:215], 0
	v_mfma_f32_16x16x32_bf16 v[76:79], v[160:163], v[212:215], 0
	v_mfma_f32_16x16x32_bf16 v[124:127], v[156:159], v[192:195], v[124:127]
	v_mfma_f32_16x16x32_bf16 v[120:123], v[164:167], v[192:195], v[120:123]
	v_mfma_f32_16x16x32_bf16 v[116:119], v[156:159], v[200:203], v[116:119]
	v_mfma_f32_16x16x32_bf16 v[108:111], v[164:167], v[200:203], v[108:111]
	v_mfma_f32_16x16x32_bf16 v[100:103], v[156:159], v[208:211], v[100:103]
	v_mfma_f32_16x16x32_bf16 v[92:95], v[164:167], v[208:211], v[92:95]
	v_mfma_f32_16x16x32_bf16 v[84:87], v[156:159], v[216:219], v[84:87]
	v_mfma_f32_16x16x32_bf16 v[76:79], v[164:167], v[216:219], v[76:79]
	s_setprio 0
	s_setprio 1
	v_mfma_f32_16x16x32_bf16 v[112:115], v[168:171], v[188:191], 0
	v_mfma_f32_16x16x32_bf16 v[104:107], v[176:179], v[188:191], 0
	v_mfma_f32_16x16x32_bf16 v[96:99], v[168:171], v[196:199], 0
	v_mfma_f32_16x16x32_bf16 v[88:91], v[176:179], v[196:199], 0
	v_mfma_f32_16x16x32_bf16 v[80:83], v[168:171], v[204:207], 0
	v_mfma_f32_16x16x32_bf16 v[72:75], v[176:179], v[204:207], 0
	v_mfma_f32_16x16x32_bf16 v[68:71], v[168:171], v[212:215], 0
	v_mfma_f32_16x16x32_bf16 v[64:67], v[176:179], v[212:215], 0
	v_mfma_f32_16x16x32_bf16 v[112:115], v[172:175], v[192:195], v[112:115]
	v_mfma_f32_16x16x32_bf16 v[104:107], v[184:187], v[192:195], v[104:107]
	v_mfma_f32_16x16x32_bf16 v[96:99], v[172:175], v[200:203], v[96:99]
	v_mfma_f32_16x16x32_bf16 v[88:91], v[184:187], v[200:203], v[88:91]
	v_mfma_f32_16x16x32_bf16 v[80:83], v[172:175], v[208:211], v[80:83]
	v_mfma_f32_16x16x32_bf16 v[72:75], v[184:187], v[208:211], v[72:75]
	v_mfma_f32_16x16x32_bf16 v[68:71], v[172:175], v[216:219], v[68:71]
	v_mfma_f32_16x16x32_bf16 v[64:67], v[184:187], v[216:219], v[64:67]
	s_setprio 0
	s_barrier
	s_add_i32 s54, s72, s64
	v_lshl_add_u64 v[144:145], s[58:59], 0, v[130:131]
	s_mov_b32 m0, s54
	ds_read_b128 v[188:191], v151 offset:16384
	ds_read_b128 v[192:195], v151 offset:17408
	ds_read_b128 v[196:199], v151 offset:18432
	ds_read_b128 v[200:203], v151 offset:19456
	ds_read_b128 v[204:207], v151 offset:20480
	ds_read_b128 v[208:211], v151 offset:21504
	ds_read_b128 v[212:215], v151 offset:22528
	ds_read_b128 v[216:219], v151 offset:23552
	global_load_lds_dwordx4 v[144:145], off
	s_add_i32 m0, s54, 0x2000
	s_add_u32 s54, s58, 0xb0000
	v_lshl_add_u64 v[220:221], s[58:59], 0, v[134:135]
	s_addc_u32 s55, s59, 0
	s_add_i32 s79, s73, s64
	global_load_lds_dwordx4 v[220:221], off
	v_lshl_add_u64 v[222:223], s[54:55], 0, v[130:131]
	s_mov_b32 m0, s79
	v_lshl_add_u64 v[224:225], s[60:61], 0, v[132:133]
	global_load_lds_dwordx4 v[222:223], off
	v_lshl_add_u64 v[222:223], s[54:55], 0, v[134:135]
	s_add_i32 m0, s79, 0x2000
	s_nop 0
	global_load_lds_dwordx4 v[222:223], off
	v_lshl_add_u64 v[222:223], s[60:61], 0, v[128:129]
	s_mov_b32 m0, s65
	s_nop 0
	global_load_lds_dwordx4 v[222:223], off
	s_mov_b32 m0, s66
	s_nop 0
	global_load_lds_dwordx4 v[224:225], off
	s_cmp_eq_u32 s98, 0
	s_cbranch_scc1 .Lpw8_8
	s_waitcnt vmcnt(24)
	s_branch .Lpwj_8

.LBB0_1152:
	s_lshl_b32 s36, s12, 5
	s_mov_b64 s[12:13], 0x80
	s_and_b32 s74, s36, 0x60
	s_add_i32 m0, s69, 0x18000
	v_lshl_add_u64 v[6:7], v[6:7], 0, s[12:13]
	s_lshl_b32 s17, s16, 13
	s_lshl_b32 s37, s74, 7
	s_waitcnt vmcnt(2)
	s_barrier
	global_load_lds_dwordx4 v[6:7], off
	v_lshl_add_u64 v[4:5], v[4:5], 0, s[12:13]
	s_add_i32 m0, s69, 0x1a000
	s_add_i32 s75, s69, 0x8000
	s_add_i32 s76, s69, 0xa000
	global_load_lds_dwordx4 v[4:5], off
	v_lshl_add_u64 v[0:1], v[0:1], 0, s[12:13]
	s_mov_b32 m0, s75
	s_add_u32 s18, s62, 0x40080
	global_load_lds_dwordx4 v[0:1], off
	v_lshl_add_u64 v[0:1], v[2:3], 0, s[12:13]
	s_mov_b32 m0, s76
	s_addc_u32 s19, s63, 0
	global_load_lds_dwordx4 v[0:1], off
	s_add_i32 m0, s69, 0x1c000
	v_lshl_add_u64 v[0:1], s[18:19], 0, v[130:131]
	global_load_lds_dwordx4 v[0:1], off
	v_lshl_add_u64 v[0:1], s[18:19], 0, v[134:135]
	s_add_i32 m0, s69, 0x1e000
	s_cmpk_lt_u32 s11, 0x100
	global_load_lds_dwordx4 v[0:1], off
	v_lshrrev_b32_e32 v1, 1, v8
	v_and_b32_e32 v1, 24, v1
	v_and_b32_e32 v0, 15, v8
	v_lshlrev_b32_e32 v2, 1, v1
	v_lshl_or_b32 v146, s16, 6, v0
	v_lshl_or_b32 v0, v0, 6, v2
	v_lshlrev_b32_e32 v2, 2, v8
	v_and_b32_e32 v2, 32, v2
	v_bitop3_b32 v3, v0, s17, v2 bitop3:0xde
	v_bitop3_b32 v147, v0, s37, v2 bitop3:0xde
	v_and_or_b32 v0, s36, 32, v1
	v_lshlrev_b32_e32 v0, 1, v0
	v_mov_b32_e32 v1, v131
	v_lshl_add_u64 v[136:137], s[22:23], 0, v[0:1]
	v_lshlrev_b32_e32 v0, 14, v9
	v_and_b32_e32 v0, 0xffff8000, v0
	v_lshl_add_u32 v0, v10, 11, v0
	v_and_b32_e32 v1, 1, v9
	v_lshl_or_b32 v0, v1, 6, v0
	v_lshl_add_u32 v138, v11, 1, v0
	v_lshlrev_b32_e32 v0, 14, v12
	v_and_b32_e32 v0, 0xffff8000, v0
	s_waitcnt vmcnt(6)
	v_lshl_add_u32 v0, v13, 11, v0
	v_and_b32_e32 v1, 1, v12
	s_cselect_b64 s[16:17], -1, 0
	v_lshl_or_b32 v0, v1, 6, v0
	s_add_i32 s77, 0, 0x10000
	s_add_i32 s82, 0, 0x14000
	s_sext_i32_i8 s59, s10
	v_mov_b32_e32 v139, v131
	v_lshl_add_u32 v140, v14, 1, v0
	v_mov_b32_e32 v141, v131
	v_mov_b64_e32 v[142:143], 0x200
	v_mov_b64_e32 v[144:145], 0x1ff
	v_add_u32_e32 v148, s77, v147
	v_add_u32_e32 v149, s82, v147
	v_add_u32_e32 v150, 0, v3
	s_mov_b64 s[18:19], 0x4000
	s_mov_b64 s[36:37], 0x4800
	s_mov_b64 s[44:45], 0x5000
	s_mov_b64 s[46:47], 0x5800
	v_mov_b32_e32 v151, 0x3e38aa3b
	s_barrier
	s_mov_b32 s98, 0
	s_branch .LBB0_1155

.LBB0_1161:
	s_ashr_i32 s53, s52, 31
	s_lshl_b64 s[54:55], s[52:53], 19
	s_add_u32 s54, s80, s54
	s_addc_u32 s55, s81, s55
	s_and_b64 s[56:57], s[10:11], exec
	s_cselect_b32 s53, s55, s61
	s_cselect_b32 s83, s54, s60
	s_ashr_i32 s49, s48, 31
	s_lshl_b64 s[56:57], s[48:49], 19
	s_add_u32 s56, s66, s56
	s_addc_u32 s57, s67, s57
	s_and_b64 s[64:65], s[10:11], exec
	s_cselect_b32 s49, s57, s63
	s_cselect_b32 s84, s56, s62
	s_add_u32 s60, s60, 0x40080
	s_addc_u32 s61, s61, 0
	s_add_u32 s85, s62, 0x100
	s_addc_u32 s86, s63, 0
	s_mov_b32 s87, -2
	ds_read_b128 v[152:155], v148
	ds_read_b128 v[156:159], v148 offset:1024
	ds_read_b128 v[160:163], v148 offset:2048
	ds_read_b128 v[164:167], v148 offset:3072
	ds_read_b128 v[168:171], v149
	ds_read_b128 v[172:175], v149 offset:1024
	ds_read_b128 v[176:179], v149 offset:2048
	ds_read_b128 v[184:187], v149 offset:3072
	s_add_u32 s62, s60, 0xfffc0080
	s_addc_u32 s63, s61, -1
	s_cmp_eq_u32 s87, 12
	s_cselect_b32 s65, s53, s63
	s_cselect_b32 s64, s83, s62
	s_cselect_b32 s63, s49, s86
	s_cselect_b32 s62, s84, s85
	v_lshl_add_u64 v[220:221], s[60:61], 0, v[138:139]
	s_add_i32 m0, s69, 0xc000
	ds_read_b128 v[188:191], v150
	ds_read_b128 v[192:195], v150 offset:1024
	ds_read_b128 v[196:199], v150 offset:2048
	ds_read_b128 v[200:203], v150 offset:3072
	ds_read_b128 v[204:207], v150 offset:4096
	ds_read_b128 v[208:211], v150 offset:5120
	ds_read_b128 v[212:215], v150 offset:6144
	ds_read_b128 v[216:219], v150 offset:7168
	global_load_lds_dwordx4 v[220:221], off
	v_lshl_add_u64 v[220:221], s[60:61], 0, v[140:141]
	s_add_i32 m0, s69, 0xe000
	s_nop 0
	global_load_lds_dwordx4 v[220:221], off
	s_waitcnt vmcnt(24)
	s_waitcnt lgkmcnt(0)
	s_barrier
	s_setprio 1
	s_waitcnt lgkmcnt(0)
	v_mfma_f32_16x16x32_bf16 v[124:127], v[152:155], v[188:191], 0
	v_mfma_f32_16x16x32_bf16 v[120:123], v[160:163], v[188:191], 0
	v_mfma_f32_16x16x32_bf16 v[116:119], v[152:155], v[196:199], 0
	v_mfma_f32_16x16x32_bf16 v[112:115], v[160:163], v[196:199], 0
	v_mfma_f32_16x16x32_bf16 v[108:111], v[152:155], v[204:207], 0
	v_mfma_f32_16x16x32_bf16 v[104:107], v[160:163], v[204:207], 0
	v_mfma_f32_16x16x32_bf16 v[100:103], v[152:155], v[212:215], 0
	v_mfma_f32_16x16x32_bf16 v[96:99], v[160:163], v[212:215], 0
	v_mfma_f32_16x16x32_bf16 v[124:127], v[156:159], v[192:195], v[124:127]
	v_mfma_f32_16x16x32_bf16 v[120:123], v[164:167], v[192:195], v[120:123]
	v_mfma_f32_16x16x32_bf16 v[116:119], v[156:159], v[200:203], v[116:119]
	v_mfma_f32_16x16x32_bf16 v[112:115], v[164:167], v[200:203], v[112:115]
	v_mfma_f32_16x16x32_bf16 v[108:111], v[156:159], v[208:211], v[108:111]
	v_mfma_f32_16x16x32_bf16 v[104:107], v[164:167], v[208:211], v[104:107]
	v_mfma_f32_16x16x32_bf16 v[100:103], v[156:159], v[216:219], v[100:103]
	v_mfma_f32_16x16x32_bf16 v[96:99], v[164:167], v[216:219], v[96:99]
	s_setprio 0
	s_setprio 1
	v_mfma_f32_16x16x32_bf16 v[68:71], v[168:171], v[188:191], 0
	v_mfma_f32_16x16x32_bf16 v[64:67], v[176:179], v[188:191], 0
	v_mfma_f32_16x16x32_bf16 v[52:55], v[168:171], v[196:199], 0
	v_mfma_f32_16x16x32_bf16 v[48:51], v[176:179], v[196:199], 0
	v_mfma_f32_16x16x32_bf16 v[44:47], v[168:171], v[204:207], 0
	v_mfma_f32_16x16x32_bf16 v[40:43], v[176:179], v[204:207], 0
	v_mfma_f32_16x16x32_bf16 v[36:39], v[168:171], v[212:215], 0
	v_mfma_f32_16x16x32_bf16 v[32:35], v[176:179], v[212:215], 0
	v_mfma_f32_16x16x32_bf16 v[68:71], v[172:175], v[192:195], v[68:71]
	v_mfma_f32_16x16x32_bf16 v[64:67], v[184:187], v[192:195], v[64:67]
	v_mfma_f32_16x16x32_bf16 v[52:55], v[172:175], v[200:203], v[52:55]
	v_mfma_f32_16x16x32_bf16 v[48:51], v[184:187], v[200:203], v[48:51]
	v_mfma_f32_16x16x32_bf16 v[44:47], v[172:175], v[208:211], v[44:47]
	v_mfma_f32_16x16x32_bf16 v[40:43], v[184:187], v[208:211], v[40:43]
	v_mfma_f32_16x16x32_bf16 v[36:39], v[172:175], v[216:219], v[36:39]
	v_mfma_f32_16x16x32_bf16 v[32:35], v[184:187], v[216:219], v[32:35]
	s_setprio 0
	s_barrier
	s_add_i32 s79, s77, s68
	v_lshl_add_u64 v[220:221], s[62:63], 0, v[130:131]
	s_mov_b32 m0, s79
	ds_read_b128 v[188:191], v150 offset:16384
	ds_read_b128 v[192:195], v150 offset:17408
	ds_read_b128 v[196:199], v150 offset:18432
	ds_read_b128 v[200:203], v150 offset:19456
	ds_read_b128 v[204:207], v150 offset:20480
	ds_read_b128 v[208:211], v150 offset:21504
	ds_read_b128 v[212:215], v150 offset:22528
	ds_read_b128 v[216:219], v150 offset:23552
	global_load_lds_dwordx4 v[220:221], off
	s_add_i32 m0, s79, 0x2000
	s_add_u32 s88, s62, 0x40000
	v_lshl_add_u64 v[222:223], s[62:63], 0, v[134:135]
	s_addc_u32 s89, s63, 0
	s_add_i32 s79, s82, s68
	global_load_lds_dwordx4 v[222:223], off
	v_lshl_add_u64 v[224:225], s[88:89], 0, v[130:131]
	s_mov_b32 m0, s79
	v_lshl_add_u64 v[226:227], s[64:65], 0, v[132:133]
	global_load_lds_dwordx4 v[224:225], off
	v_lshl_add_u64 v[224:225], s[88:89], 0, v[134:135]
	s_add_i32 m0, s79, 0x2000
	s_nop 0
	global_load_lds_dwordx4 v[224:225], off
	v_lshl_add_u64 v[224:225], s[64:65], 0, v[128:129]
	s_mov_b32 m0, s69
	s_nop 0
	global_load_lds_dwordx4 v[224:225], off
	s_mov_b32 m0, s70
	s_nop 0
	global_load_lds_dwordx4 v[226:227], off
	s_cmp_eq_u32 s98, 0
	s_cbranch_scc1 .Lpw8_9
	s_waitcnt vmcnt(24)
	s_branch .Lpwj_9

.LBB0_1301:
	s_lshl_b32 s16, s16, 5
	s_and_b32 s36, s16, 0x60
	s_mov_b64 s[16:17], 0x80
	s_add_i32 m0, s55, 0x18000
	v_lshl_add_u64 v[6:7], v[6:7], 0, s[16:17]
	s_lshl_b32 s19, s18, 13
	s_lshl_b32 s37, s36, 7
	s_waitcnt vmcnt(2)
	s_barrier
	global_load_lds_dwordx4 v[6:7], off
	v_lshl_add_u64 v[2:3], v[2:3], 0, s[16:17]
	s_add_i32 m0, s55, 0x1a000
	s_add_i32 s69, s55, 0x8000
	s_add_i32 s70, s55, 0xa000
	global_load_lds_dwordx4 v[2:3], off
	v_lshl_add_u64 v[0:1], v[0:1], 0, s[16:17]
	s_mov_b32 m0, s69
	s_add_u32 s30, s58, 0x40080
	global_load_lds_dwordx4 v[0:1], off
	v_lshl_add_u64 v[0:1], v[4:5], 0, s[16:17]
	s_mov_b32 m0, s70
	s_addc_u32 s31, s59, 0
	global_load_lds_dwordx4 v[0:1], off
	s_add_i32 m0, s55, 0x1c000
	v_lshl_add_u64 v[0:1], s[30:31], 0, v[130:131]
	global_load_lds_dwordx4 v[0:1], off
	v_lshl_add_u64 v[0:1], s[30:31], 0, v[134:135]
	s_add_i32 m0, s55, 0x1e000
	s_cmpk_lt_u32 s11, 0x100
	global_load_lds_dwordx4 v[0:1], off
	v_lshrrev_b32_e32 v1, 1, v8
	v_and_b32_e32 v1, 24, v1
	v_and_b32_e32 v0, 15, v8
	v_lshlrev_b32_e32 v2, 1, v1
	v_lshl_or_b32 v146, s18, 6, v0
	v_lshl_or_b32 v0, v0, 6, v2
	v_lshlrev_b32_e32 v2, 2, v8
	v_and_b32_e32 v2, 32, v2
	v_bitop3_b32 v3, v0, s19, v2 bitop3:0xde
	v_bitop3_b32 v147, v0, s37, v2 bitop3:0xde
	v_lshlrev_b32_e32 v0, 14, v9
	v_and_b32_e32 v0, 0xffff8000, v0
	v_or_b32_e32 v148, s36, v1
	v_lshl_add_u32 v0, v10, 11, v0
	v_and_b32_e32 v1, 1, v9
	v_lshl_or_b32 v0, v1, 6, v0
	v_lshl_add_u32 v136, v11, 1, v0
	v_lshlrev_b32_e32 v0, 14, v12
	v_and_b32_e32 v0, 0xffff8000, v0
	s_waitcnt vmcnt(6)
	v_lshl_add_u32 v0, v13, 11, v0
	v_and_b32_e32 v1, 1, v12
	s_cselect_b64 s[18:19], -1, 0
	v_lshl_or_b32 v0, v1, 6, v0
	s_add_i32 s71, 0, 0x10000
	s_add_i32 s72, 0, 0x14000
	s_sext_i32_i8 s77, s10
	v_mov_b32_e32 v137, v131
	v_lshl_add_u32 v138, v14, 1, v0
	v_mov_b32_e32 v139, v131
	v_mov_b64_e32 v[140:141], 0x200
	v_mov_b64_e32 v[142:143], 0x1ff
	v_add_u32_e32 v149, s71, v147
	v_add_u32_e32 v150, s72, v147
	v_add_u32_e32 v151, 0, v3
	s_mov_b32 s73, 0x40000
	s_mov_b64 s[30:31], 0x48000
	s_mov_b32 s74, 0x48000
	s_mov_b64 s[36:37], 0x50000
	s_mov_b32 s75, 0x50000
	s_mov_b64 s[44:45], 0x58000
	s_mov_b32 s76, 0x58000
	s_barrier
	s_mov_b32 s98, 0
	s_branch .LBB0_1304

.LBB0_1303:
	s_andn2_b64 vcc, exec, s[10:11]
	s_mov_b32 s77, s46
	s_mov_b32 s54, s48
	s_mov_b64 s[58:59], s[52:53]
	s_mov_b64 s[56:57], s[50:51]
	s_mov_b32 s98, 1
	s_cbranch_vccz .LBB0_1317

.LBB0_1310:
	s_ashr_i32 s49, s48, 31
	s_lshl_b64 s[50:51], s[48:49], 19
	s_add_u32 s50, s38, s50
	s_addc_u32 s51, s39, s51
	s_and_b64 s[52:53], s[10:11], exec
	s_cselect_b32 s49, s51, s57
	s_cselect_b32 s82, s50, s56
	s_ashr_i32 s47, s46, 31
	s_lshl_b64 s[52:53], s[46:47], 19
	s_add_u32 s52, s62, s52
	s_addc_u32 s53, s63, s53
	s_and_b64 s[60:61], s[10:11], exec
	s_cselect_b32 s47, s53, s59
	s_cselect_b32 s83, s52, s58
	s_add_u32 s56, s56, 0x40080
	s_addc_u32 s57, s57, 0
	s_add_u32 s84, s58, 0x100
	s_addc_u32 s85, s59, 0
	s_mov_b32 s86, -2
	ds_read_b128 v[152:155], v149
	ds_read_b128 v[156:159], v149 offset:1024
	ds_read_b128 v[160:163], v149 offset:2048
	ds_read_b128 v[164:167], v149 offset:3072
	ds_read_b128 v[168:171], v150
	ds_read_b128 v[172:175], v150 offset:1024
	ds_read_b128 v[176:179], v150 offset:2048
	ds_read_b128 v[184:187], v150 offset:3072
	s_add_u32 s58, s56, 0xfffc0080
	s_addc_u32 s59, s57, -1
	s_cmp_eq_u32 s86, 12
	s_cselect_b32 s61, s49, s59
	s_cselect_b32 s60, s82, s58
	s_cselect_b32 s59, s47, s85
	s_cselect_b32 s58, s83, s84
	v_lshl_add_u64 v[144:145], s[56:57], 0, v[136:137]
	s_add_i32 m0, s55, 0xc000
	ds_read_b128 v[188:191], v151
	ds_read_b128 v[192:195], v151 offset:1024
	ds_read_b128 v[196:199], v151 offset:2048
	ds_read_b128 v[200:203], v151 offset:3072
	ds_read_b128 v[204:207], v151 offset:4096
	ds_read_b128 v[208:211], v151 offset:5120
	ds_read_b128 v[212:215], v151 offset:6144
	ds_read_b128 v[216:219], v151 offset:7168
	global_load_lds_dwordx4 v[144:145], off
	v_lshl_add_u64 v[144:145], s[56:57], 0, v[138:139]
	s_add_i32 m0, s55, 0xe000
	s_nop 0
	global_load_lds_dwordx4 v[144:145], off
	s_waitcnt vmcnt(24)
	s_waitcnt lgkmcnt(0)
	s_barrier
	s_setprio 1
	s_waitcnt lgkmcnt(0)
	v_mfma_f32_16x16x32_bf16 v[124:127], v[152:155], v[188:191], 0
	v_mfma_f32_16x16x32_bf16 v[120:123], v[160:163], v[188:191], 0
	v_mfma_f32_16x16x32_bf16 v[116:119], v[152:155], v[196:199], 0
	v_mfma_f32_16x16x32_bf16 v[108:111], v[160:163], v[196:199], 0
	v_mfma_f32_16x16x32_bf16 v[100:103], v[152:155], v[204:207], 0
	v_mfma_f32_16x16x32_bf16 v[92:95], v[160:163], v[204:207], 0
	v_mfma_f32_16x16x32_bf16 v[84:87], v[152:155], v[212:215], 0
	v_mfma_f32_16x16x32_bf16 v[76:79], v[160:163], v[212:215], 0
	v_mfma_f32_16x16x32_bf16 v[124:127], v[156:159], v[192:195], v[124:127]
	v_mfma_f32_16x16x32_bf16 v[120:123], v[164:167], v[192:195], v[120:123]
	v_mfma_f32_16x16x32_bf16 v[116:119], v[156:159], v[200:203], v[116:119]
	v_mfma_f32_16x16x32_bf16 v[108:111], v[164:167], v[200:203], v[108:111]
	v_mfma_f32_16x16x32_bf16 v[100:103], v[156:159], v[208:211], v[100:103]
	v_mfma_f32_16x16x32_bf16 v[92:95], v[164:167], v[208:211], v[92:95]
	v_mfma_f32_16x16x32_bf16 v[84:87], v[156:159], v[216:219], v[84:87]
	v_mfma_f32_16x16x32_bf16 v[76:79], v[164:167], v[216:219], v[76:79]
	s_setprio 0
	s_setprio 1
	v_mfma_f32_16x16x32_bf16 v[112:115], v[168:171], v[188:191], 0
	v_mfma_f32_16x16x32_bf16 v[104:107], v[176:179], v[188:191], 0
	v_mfma_f32_16x16x32_bf16 v[96:99], v[168:171], v[196:199], 0
	v_mfma_f32_16x16x32_bf16 v[88:91], v[176:179], v[196:199], 0
	v_mfma_f32_16x16x32_bf16 v[80:83], v[168:171], v[204:207], 0
	v_mfma_f32_16x16x32_bf16 v[72:75], v[176:179], v[204:207], 0
	v_mfma_f32_16x16x32_bf16 v[68:71], v[168:171], v[212:215], 0
	v_mfma_f32_16x16x32_bf16 v[64:67], v[176:179], v[212:215], 0
	v_mfma_f32_16x16x32_bf16 v[112:115], v[172:175], v[192:195], v[112:115]
	v_mfma_f32_16x16x32_bf16 v[104:107], v[184:187], v[192:195], v[104:107]
	v_mfma_f32_16x16x32_bf16 v[96:99], v[172:175], v[200:203], v[96:99]
	v_mfma_f32_16x16x32_bf16 v[88:91], v[184:187], v[200:203], v[88:91]
	v_mfma_f32_16x16x32_bf16 v[80:83], v[172:175], v[208:211], v[80:83]
	v_mfma_f32_16x16x32_bf16 v[72:75], v[184:187], v[208:211], v[72:75]
	v_mfma_f32_16x16x32_bf16 v[68:71], v[172:175], v[216:219], v[68:71]
	v_mfma_f32_16x16x32_bf16 v[64:67], v[184:187], v[216:219], v[64:67]
	s_setprio 0
	s_barrier
	s_add_i32 s79, s71, s64
	v_lshl_add_u64 v[144:145], s[58:59], 0, v[130:131]
	s_mov_b32 m0, s79
	ds_read_b128 v[188:191], v151 offset:16384
	ds_read_b128 v[192:195], v151 offset:17408
	ds_read_b128 v[196:199], v151 offset:18432
	ds_read_b128 v[200:203], v151 offset:19456
	ds_read_b128 v[204:207], v151 offset:20480
	ds_read_b128 v[208:211], v151 offset:21504
	ds_read_b128 v[212:215], v151 offset:22528
	ds_read_b128 v[216:219], v151 offset:23552
	global_load_lds_dwordx4 v[144:145], off
	s_add_i32 m0, s79, 0x2000
	s_add_u32 s88, s58, 0x40000
	v_lshl_add_u64 v[220:221], s[58:59], 0, v[134:135]
	s_addc_u32 s89, s59, 0
	s_add_i32 s79, s72, s64
	global_load_lds_dwordx4 v[220:221], off
	v_lshl_add_u64 v[222:223], s[88:89], 0, v[130:131]
	s_mov_b32 m0, s79
	v_lshl_add_u64 v[224:225], s[60:61], 0, v[132:133]
	global_load_lds_dwordx4 v[222:223], off
	v_lshl_add_u64 v[222:223], s[88:89], 0, v[134:135]
	s_add_i32 m0, s79, 0x2000
	s_nop 0
	global_load_lds_dwordx4 v[222:223], off
	v_lshl_add_u64 v[222:223], s[60:61], 0, v[128:129]
	s_mov_b32 m0, s55
	s_nop 0
	global_load_lds_dwordx4 v[222:223], off
	s_mov_b32 m0, s65
	s_nop 0
	global_load_lds_dwordx4 v[224:225], off
	s_cmp_eq_u32 s98, 0
	s_cbranch_scc1 .Lpw8_10
	s_waitcnt vmcnt(24)
	s_branch .Lpwj_10

.LBB0_1428:
	s_and_b32 s18, s10, 3
	s_mov_b64 s[10:11], 0x80
	s_add_i32 m0, s45, 0x18000
	v_lshl_add_u64 v[6:7], v[6:7], 0, s[10:11]
	s_lshl_b32 s13, s12, 13
	s_lshl_b32 s19, s18, 12
	s_waitcnt vmcnt(2)
	s_barrier
	global_load_lds_dwordx4 v[6:7], off
	v_lshl_add_u64 v[4:5], v[4:5], 0, s[10:11]
	s_add_i32 m0, s45, 0x1a000
	s_add_i32 s60, s45, 0x8000
	s_add_i32 s61, s45, 0xa000
	global_load_lds_dwordx4 v[4:5], off
	v_lshl_add_u64 v[0:1], v[0:1], 0, s[10:11]
	s_mov_b32 m0, s60
	s_add_u32 s16, s48, 0x40080
	global_load_lds_dwordx4 v[0:1], off
	v_lshl_add_u64 v[0:1], v[2:3], 0, s[10:11]
	s_mov_b32 m0, s61
	s_addc_u32 s17, s49, 0
	global_load_lds_dwordx4 v[0:1], off
	s_add_i32 m0, s45, 0x1c000
	v_lshl_add_u64 v[0:1], s[16:17], 0, v[130:131]
	global_load_lds_dwordx4 v[0:1], off
	v_lshl_add_u64 v[0:1], s[16:17], 0, v[128:129]
	s_add_i32 m0, s45, 0x1e000
	s_cmpk_lt_u32 s9, 0x100
	global_load_lds_dwordx4 v[0:1], off
	v_bfe_u32 v1, v9, 4, 2
	v_and_b32_e32 v0, 15, v9
	v_lshlrev_b32_e32 v2, 4, v1
	v_lshl_or_b32 v144, s12, 6, v0
	v_lshl_or_b32 v0, v0, 6, v2
	v_lshlrev_b32_e32 v2, 2, v9
	v_and_b32_e32 v2, 32, v2
	v_bitop3_b32 v3, v0, s13, v2 bitop3:0xde
	v_bitop3_b32 v145, v0, s19, v2 bitop3:0xde
	v_lshlrev_b32_e32 v0, 2, v1
	v_lshl_or_b32 v146, s18, 4, v0
	v_lshlrev_b32_e32 v0, 14, v12
	v_and_b32_e32 v0, 0xffff8000, v0
	v_lshl_add_u32 v0, v13, 11, v0
	v_and_b32_e32 v1, 1, v12
	v_lshl_or_b32 v0, v1, 6, v0
	v_lshl_add_u32 v132, v14, 1, v0
	v_lshlrev_b32_e32 v0, 14, v8
	v_and_b32_e32 v0, 0xffff8000, v0
	s_waitcnt vmcnt(6)
	v_lshl_add_u32 v0, v10, 11, v0
	v_and_b32_e32 v1, 1, v8
	s_cselect_b64 s[12:13], -1, 0
	v_lshl_or_b32 v0, v1, 6, v0
	s_add_i32 s62, 0, 0x10000
	s_add_i32 s63, 0, 0x14000
	s_sext_i32_i16 s65, s8
	v_mov_b32_e32 v133, v131
	v_lshl_add_u32 v134, v11, 1, v0
	v_mov_b32_e32 v135, v131
	v_mov_b64_e32 v[136:137], 0xb00
	v_mov_b64_e32 v[138:139], 0xaff
	v_add_u32_e32 v147, s62, v145
	v_add_u32_e32 v148, s63, v145
	v_add_u32_e32 v149, 0, v3
	s_movk_i32 s64, 0x1600
	s_barrier
	s_mov_b32 s98, 0
	s_branch .LBB0_1431

.LBB0_1430:
	s_andn2_b64 vcc, exec, s[8:9]
	s_mov_b32 s65, s16
	s_mov_b32 s44, s18
	s_mov_b64 s[48:49], s[36:37]
	s_mov_b64 s[46:47], s[30:31]
	s_mov_b32 s98, 1
	s_cbranch_vccz .LBB0_1440

.LBB0_1433:
	s_ashr_i32 s19, s18, 31
	s_lshl_b64 s[30:31], s[18:19], 19
	s_add_u32 s30, s80, s30
	s_addc_u32 s31, s81, s31
	s_and_b64 s[36:37], s[8:9], exec
	s_cselect_b32 s19, s31, s47
	s_cselect_b32 s66, s30, s46
	s_ashr_i32 s17, s16, 31
	s_lshl_b64 s[36:37], s[16:17], 19
	s_add_u32 s36, s52, s36
	s_addc_u32 s37, s53, s37
	s_and_b64 s[50:51], s[8:9], exec
	s_cselect_b32 s17, s37, s49
	s_cselect_b32 s67, s36, s48
	s_add_u32 s46, s46, 0x40080
	s_addc_u32 s47, s47, 0
	s_add_u32 s68, s48, 0x100
	s_addc_u32 s69, s49, 0
	s_mov_b32 s70, -2
	ds_read_b128 v[140:143], v147
	ds_read_b128 v[150:153], v147 offset:1024
	ds_read_b128 v[154:157], v147 offset:2048
	ds_read_b128 v[158:161], v147 offset:3072
	ds_read_b128 v[162:165], v148
	ds_read_b128 v[166:169], v148 offset:1024
	ds_read_b128 v[170:173], v148 offset:2048
	ds_read_b128 v[174:177], v148 offset:3072
	s_add_u32 s48, s46, 0xfffc0080
	s_addc_u32 s49, s47, -1
	s_cmp_eq_u32 s70, 12
	s_cselect_b32 s51, s19, s49
	s_cselect_b32 s50, s66, s48
	s_cselect_b32 s49, s17, s69
	s_cselect_b32 s48, s67, s68
	v_lshl_add_u64 v[178:179], s[46:47], 0, v[132:133]
	s_add_i32 m0, s45, 0xc000
	ds_read_b128 v[184:187], v149
	ds_read_b128 v[188:191], v149 offset:1024
	ds_read_b128 v[192:195], v149 offset:2048
	ds_read_b128 v[196:199], v149 offset:3072
	ds_read_b128 v[200:203], v149 offset:4096
	ds_read_b128 v[204:207], v149 offset:5120
	ds_read_b128 v[208:211], v149 offset:6144
	ds_read_b128 v[212:215], v149 offset:7168
	global_load_lds_dwordx4 v[178:179], off
	v_lshl_add_u64 v[178:179], s[46:47], 0, v[134:135]
	s_add_i32 m0, s45, 0xe000
	s_nop 0
	global_load_lds_dwordx4 v[178:179], off
	s_waitcnt vmcnt(24)
	s_waitcnt lgkmcnt(0)
	s_barrier
	s_setprio 1
	s_waitcnt lgkmcnt(0)
	v_mfma_f32_16x16x32_bf16 v[124:127], v[140:143], v[184:187], 0
	v_mfma_f32_16x16x32_bf16 v[120:123], v[154:157], v[184:187], 0
	v_mfma_f32_16x16x32_bf16 v[108:111], v[140:143], v[192:195], 0
	v_mfma_f32_16x16x32_bf16 v[104:107], v[154:157], v[192:195], 0
	v_mfma_f32_16x16x32_bf16 v[92:95], v[140:143], v[200:203], 0
	v_mfma_f32_16x16x32_bf16 v[88:91], v[154:157], v[200:203], 0
	v_mfma_f32_16x16x32_bf16 v[76:79], v[140:143], v[208:211], 0
	v_mfma_f32_16x16x32_bf16 v[72:75], v[154:157], v[208:211], 0
	v_mfma_f32_16x16x32_bf16 v[124:127], v[150:153], v[188:191], v[124:127]
	v_mfma_f32_16x16x32_bf16 v[120:123], v[158:161], v[188:191], v[120:123]
	v_mfma_f32_16x16x32_bf16 v[108:111], v[150:153], v[196:199], v[108:111]
	v_mfma_f32_16x16x32_bf16 v[104:107], v[158:161], v[196:199], v[104:107]
	v_mfma_f32_16x16x32_bf16 v[92:95], v[150:153], v[204:207], v[92:95]
	v_mfma_f32_16x16x32_bf16 v[88:91], v[158:161], v[204:207], v[88:91]
	v_mfma_f32_16x16x32_bf16 v[76:79], v[150:153], v[212:215], v[76:79]
	v_mfma_f32_16x16x32_bf16 v[72:75], v[158:161], v[212:215], v[72:75]
	s_setprio 0
	s_setprio 1
	v_mfma_f32_16x16x32_bf16 v[116:119], v[162:165], v[184:187], 0
	v_mfma_f32_16x16x32_bf16 v[112:115], v[170:173], v[184:187], 0
	v_mfma_f32_16x16x32_bf16 v[100:103], v[162:165], v[192:195], 0
	v_mfma_f32_16x16x32_bf16 v[96:99], v[170:173], v[192:195], 0
	v_mfma_f32_16x16x32_bf16 v[84:87], v[162:165], v[200:203], 0
	v_mfma_f32_16x16x32_bf16 v[80:83], v[170:173], v[200:203], 0
	v_mfma_f32_16x16x32_bf16 v[68:71], v[162:165], v[208:211], 0
	v_mfma_f32_16x16x32_bf16 v[64:67], v[170:173], v[208:211], 0
	v_mfma_f32_16x16x32_bf16 v[116:119], v[166:169], v[188:191], v[116:119]
	v_mfma_f32_16x16x32_bf16 v[112:115], v[174:177], v[188:191], v[112:115]
	v_mfma_f32_16x16x32_bf16 v[100:103], v[166:169], v[196:199], v[100:103]
	v_mfma_f32_16x16x32_bf16 v[96:99], v[174:177], v[196:199], v[96:99]
	v_mfma_f32_16x16x32_bf16 v[84:87], v[166:169], v[204:207], v[84:87]
	v_mfma_f32_16x16x32_bf16 v[80:83], v[174:177], v[204:207], v[80:83]
	v_mfma_f32_16x16x32_bf16 v[68:71], v[166:169], v[212:215], v[68:71]
	v_mfma_f32_16x16x32_bf16 v[64:67], v[174:177], v[212:215], v[64:67]
	s_setprio 0
	s_barrier
	s_add_i32 s71, s62, s54
	v_lshl_add_u64 v[178:179], s[48:49], 0, v[130:131]
	s_mov_b32 m0, s71
	ds_read_b128 v[184:187], v149 offset:16384
	ds_read_b128 v[188:191], v149 offset:17408
	ds_read_b128 v[192:195], v149 offset:18432
	ds_read_b128 v[196:199], v149 offset:19456
	ds_read_b128 v[200:203], v149 offset:20480
	ds_read_b128 v[204:207], v149 offset:21504
	ds_read_b128 v[208:211], v149 offset:22528
	ds_read_b128 v[212:215], v149 offset:23552
	global_load_lds_dwordx4 v[178:179], off
	s_add_i32 m0, s71, 0x2000
	s_add_u32 s72, s48, 0x40000
	v_lshl_add_u64 v[216:217], s[48:49], 0, v[128:129]
	s_addc_u32 s73, s49, 0
	s_add_i32 s71, s63, s54
	global_load_lds_dwordx4 v[216:217], off
	v_lshl_add_u64 v[218:219], s[72:73], 0, v[130:131]
	s_mov_b32 m0, s71
	v_lshl_add_u64 v[220:221], s[50:51], 0, v[128:129]
	global_load_lds_dwordx4 v[218:219], off
	v_lshl_add_u64 v[218:219], s[72:73], 0, v[128:129]
	s_add_i32 m0, s71, 0x2000
	s_nop 0
	global_load_lds_dwordx4 v[218:219], off
	v_lshl_add_u64 v[218:219], s[50:51], 0, v[130:131]
	s_mov_b32 m0, s45
	s_nop 0
	global_load_lds_dwordx4 v[218:219], off
	s_mov_b32 m0, s56
	s_nop 0
	global_load_lds_dwordx4 v[220:221], off
	s_cmp_eq_u32 s98, 0
	s_cbranch_scc1 .Lpw8_11
	s_waitcnt vmcnt(24)
	s_branch .Lpwj_11

.LBB0_1500:
	s_lshl_b32 s8, s8, 5
	s_mov_b64 s[10:11], 0x80
	s_and_b32 s18, s8, 0x60
	s_add_i32 m0, s57, 0x18000
	v_lshl_add_u64 v[6:7], v[6:7], 0, s[10:11]
	s_lshl_b32 s13, s9, 13
	s_lshl_b32 s8, s18, 7
	s_waitcnt vmcnt(2)
	s_barrier
	global_load_lds_dwordx4 v[6:7], off
	v_lshl_add_u64 v[4:5], v[4:5], 0, s[10:11]
	s_add_i32 m0, s57, 0x1a000
	s_add_i32 s62, s57, 0x8000
	s_add_i32 s63, s57, 0xa000
	global_load_lds_dwordx4 v[4:5], off
	v_lshl_add_u64 v[0:1], v[0:1], 0, s[10:11]
	s_mov_b32 m0, s62
	s_add_u32 s16, s48, 0xb0080
	global_load_lds_dwordx4 v[0:1], off
	v_lshl_add_u64 v[0:1], v[2:3], 0, s[10:11]
	s_mov_b32 m0, s63
	s_addc_u32 s17, s49, 0
	global_load_lds_dwordx4 v[0:1], off
	s_add_i32 m0, s57, 0x1c000
	v_lshl_add_u64 v[0:1], s[16:17], 0, v[130:131]
	global_load_lds_dwordx4 v[0:1], off
	v_lshl_add_u64 v[0:1], s[16:17], 0, v[134:135]
	s_add_i32 m0, s57, 0x1e000
	s_cmpk_lt_u32 s6, 0x100
	global_load_lds_dwordx4 v[0:1], off
	v_lshrrev_b32_e32 v1, 1, v182
	v_and_b32_e32 v1, 24, v1
	v_and_b32_e32 v0, 15, v182
	v_lshlrev_b32_e32 v2, 1, v1
	v_lshl_or_b32 v146, s9, 6, v0
	v_lshl_or_b32 v0, v0, 6, v2
	v_lshlrev_b32_e32 v2, 2, v182
	v_and_b32_e32 v2, 32, v2
	v_bitop3_b32 v3, v0, s13, v2 bitop3:0xde
	v_bitop3_b32 v147, v0, s8, v2 bitop3:0xde
	v_or_b32_e32 v148, s18, v1
	v_lshrrev_b32_e32 v1, 1, v8
	v_mul_lo_u32 v0, v10, s7
	s_mov_b32 s6, 0xb000
	v_mad_u64_u32 v[0:1], s[16:17], v1, s6, v[0:1]
	v_or_b32_e32 v0, v0, v9
	s_mov_b64 s[8:9], 0xb0080
	v_add_lshl_u32 v0, v0, v11, 1
	v_mov_b32_e32 v1, v131
	v_lshl_add_u64 v[136:137], v[0:1], 0, s[8:9]
	v_lshrrev_b32_e32 v1, 1, v12
	v_mul_lo_u32 v0, v13, s7
	v_mad_u64_u32 v[0:1], s[6:7], v1, s6, v[0:1]
	s_waitcnt vmcnt(6)
	v_or_b32_e32 v0, v0, v14
	s_sext_i32_i8 s73, s12
	s_cselect_b64 s[12:13], -1, 0
	v_add_lshl_u32 v0, v0, v15, 1
	v_mov_b32_e32 v1, v131
	s_add_i32 s64, 0, 0x10000
	s_add_i32 s65, 0, 0x14000
	v_lshl_add_u64 v[138:139], v[0:1], 0, s[8:9]
	v_mov_b64_e32 v[140:141], 0x200
	v_mov_b64_e32 v[142:143], 0x1ff
	v_add_u32_e32 v149, s64, v147
	v_add_u32_e32 v150, s65, v147
	v_add_u32_e32 v151, 0, v3
	s_mov_b64 s[16:17], 0x40000
	s_mov_b32 s66, 0x40000
	s_mov_b64 s[18:19], 0x48000
	s_mov_b32 s67, 0x48000
	s_mov_b64 s[30:31], 0x50000
	s_mov_b32 s68, 0x50000
	s_mov_b64 s[36:37], 0x58000
	s_mov_b32 s69, 0x58000
	s_barrier
	s_mov_b32 s98, 0
	s_branch .LBB0_1503

.LBB0_1502:
	s_andn2_b64 vcc, exec, s[6:7]
	s_mov_b32 s73, s70
	s_mov_b32 s72, s71
	s_mov_b64 s[48:49], s[44:45]
	s_mov_b64 s[46:47], s[8:9]
	s_mov_b32 s98, 1
	s_cbranch_vccz .LBB0_1520

.LBB0_1513:
	s_add_u32 s74, s48, 0x100
	s_addc_u32 s75, s49, 0
	s_mov_b32 s76, -2
	ds_read_b128 v[152:155], v149
	ds_read_b128 v[156:159], v149 offset:1024
	ds_read_b128 v[160:163], v149 offset:2048
	ds_read_b128 v[164:167], v149 offset:3072
	ds_read_b128 v[168:171], v150
	ds_read_b128 v[172:175], v150 offset:1024
	ds_read_b128 v[176:179], v150 offset:2048
	ds_read_b128 v[184:187], v150 offset:3072
	s_add_u32 s48, s46, 0x100
	s_addc_u32 s49, s47, 0
	s_cmp_eq_u32 s76, 40
	s_cselect_b32 s53, s9, s49
	s_cselect_b32 s52, s8, s48
	s_cselect_b32 s51, s45, s75
	s_cselect_b32 s50, s44, s74
	v_lshl_add_u64 v[144:145], s[46:47], 0, v[136:137]
	s_add_i32 m0, s57, 0xc000
	ds_read_b128 v[188:191], v151
	ds_read_b128 v[192:195], v151 offset:1024
	ds_read_b128 v[196:199], v151 offset:2048
	ds_read_b128 v[200:203], v151 offset:3072
	ds_read_b128 v[204:207], v151 offset:4096
	ds_read_b128 v[208:211], v151 offset:5120
	ds_read_b128 v[212:215], v151 offset:6144
	ds_read_b128 v[216:219], v151 offset:7168
	global_load_lds_dwordx4 v[144:145], off
	v_lshl_add_u64 v[144:145], s[46:47], 0, v[138:139]
	s_add_i32 m0, s57, 0xe000
	s_nop 0
	global_load_lds_dwordx4 v[144:145], off
	s_waitcnt vmcnt(24)
	s_waitcnt lgkmcnt(0)
	s_barrier
	s_setprio 1
	s_waitcnt lgkmcnt(0)
	v_mfma_f32_16x16x32_bf16 v[124:127], v[152:155], v[188:191], 0
	v_mfma_f32_16x16x32_bf16 v[120:123], v[160:163], v[188:191], 0
	v_mfma_f32_16x16x32_bf16 v[116:119], v[152:155], v[196:199], 0
	v_mfma_f32_16x16x32_bf16 v[108:111], v[160:163], v[196:199], 0
	v_mfma_f32_16x16x32_bf16 v[100:103], v[152:155], v[204:207], 0
	v_mfma_f32_16x16x32_bf16 v[92:95], v[160:163], v[204:207], 0
	v_mfma_f32_16x16x32_bf16 v[84:87], v[152:155], v[212:215], 0
	v_mfma_f32_16x16x32_bf16 v[76:79], v[160:163], v[212:215], 0
	v_mfma_f32_16x16x32_bf16 v[124:127], v[156:159], v[192:195], v[124:127]
	v_mfma_f32_16x16x32_bf16 v[120:123], v[164:167], v[192:195], v[120:123]
	v_mfma_f32_16x16x32_bf16 v[116:119], v[156:159], v[200:203], v[116:119]
	v_mfma_f32_16x16x32_bf16 v[108:111], v[164:167], v[200:203], v[108:111]
	v_mfma_f32_16x16x32_bf16 v[100:103], v[156:159], v[208:211], v[100:103]
	v_mfma_f32_16x16x32_bf16 v[92:95], v[164:167], v[208:211], v[92:95]
	v_mfma_f32_16x16x32_bf16 v[84:87], v[156:159], v[216:219], v[84:87]
	v_mfma_f32_16x16x32_bf16 v[76:79], v[164:167], v[216:219], v[76:79]
	s_setprio 0
	s_setprio 1
	v_mfma_f32_16x16x32_bf16 v[112:115], v[168:171], v[188:191], 0
	v_mfma_f32_16x16x32_bf16 v[104:107], v[176:179], v[188:191], 0
	v_mfma_f32_16x16x32_bf16 v[96:99], v[168:171], v[196:199], 0
	v_mfma_f32_16x16x32_bf16 v[88:91], v[176:179], v[196:199], 0
	v_mfma_f32_16x16x32_bf16 v[80:83], v[168:171], v[204:207], 0
	v_mfma_f32_16x16x32_bf16 v[72:75], v[176:179], v[204:207], 0
	v_mfma_f32_16x16x32_bf16 v[68:71], v[168:171], v[212:215], 0
	v_mfma_f32_16x16x32_bf16 v[64:67], v[176:179], v[212:215], 0
	v_mfma_f32_16x16x32_bf16 v[112:115], v[172:175], v[192:195], v[112:115]
	v_mfma_f32_16x16x32_bf16 v[104:107], v[184:187], v[192:195], v[104:107]
	v_mfma_f32_16x16x32_bf16 v[96:99], v[172:175], v[200:203], v[96:99]
	v_mfma_f32_16x16x32_bf16 v[88:91], v[184:187], v[200:203], v[88:91]
	v_mfma_f32_16x16x32_bf16 v[80:83], v[172:175], v[208:211], v[80:83]
	v_mfma_f32_16x16x32_bf16 v[72:75], v[184:187], v[208:211], v[72:75]
	v_mfma_f32_16x16x32_bf16 v[68:71], v[172:175], v[216:219], v[68:71]
	v_mfma_f32_16x16x32_bf16 v[64:67], v[184:187], v[216:219], v[64:67]
	s_setprio 0
	s_barrier
	s_add_i32 s46, s64, s56
	v_lshl_add_u64 v[144:145], s[50:51], 0, v[130:131]
	s_mov_b32 m0, s46
	ds_read_b128 v[188:191], v151 offset:16384
	ds_read_b128 v[192:195], v151 offset:17408
	ds_read_b128 v[196:199], v151 offset:18432
	ds_read_b128 v[200:203], v151 offset:19456
	ds_read_b128 v[204:207], v151 offset:20480
	ds_read_b128 v[208:211], v151 offset:21504
	ds_read_b128 v[212:215], v151 offset:22528
	ds_read_b128 v[216:219], v151 offset:23552
	global_load_lds_dwordx4 v[144:145], off
	s_add_i32 m0, s46, 0x2000
	s_add_u32 s46, s50, 0xb0000
	v_lshl_add_u64 v[220:221], s[50:51], 0, v[134:135]
	s_addc_u32 s47, s51, 0
	s_add_i32 s77, s65, s56
	global_load_lds_dwordx4 v[220:221], off
	v_lshl_add_u64 v[222:223], s[46:47], 0, v[130:131]
	s_mov_b32 m0, s77
	v_lshl_add_u64 v[224:225], s[52:53], 0, v[132:133]
	global_load_lds_dwordx4 v[222:223], off
	v_lshl_add_u64 v[222:223], s[46:47], 0, v[134:135]
	s_add_i32 m0, s77, 0x2000
	s_nop 0
	global_load_lds_dwordx4 v[222:223], off
	v_lshl_add_u64 v[222:223], s[52:53], 0, v[128:129]
	s_mov_b32 m0, s57
	s_nop 0
	global_load_lds_dwordx4 v[222:223], off
	s_mov_b32 m0, s58
	s_nop 0
	global_load_lds_dwordx4 v[224:225], off
	s_cmp_eq_u32 s98, 0
	s_cbranch_scc1 .Lpw8_12
	s_waitcnt vmcnt(24)
	s_branch .Lpwj_12

	.amdhsa_kernel _Z8yoco_fwd4Args
		.amdhsa_group_segment_fixed_size 0
		.amdhsa_private_segment_fixed_size 0
		.amdhsa_kernarg_size 376
		.amdhsa_user_sgpr_count 2
		.amdhsa_user_sgpr_dispatch_ptr 0
		.amdhsa_user_sgpr_queue_ptr 0
		.amdhsa_user_sgpr_kernarg_segment_ptr 1
		.amdhsa_user_sgpr_dispatch_id 0
		.amdhsa_user_sgpr_kernarg_preload_length 0
		.amdhsa_user_sgpr_kernarg_preload_offset 0
		.amdhsa_user_sgpr_private_segment_size 0
		.amdhsa_uses_dynamic_stack 0
		.amdhsa_enable_private_segment 0
		.amdhsa_system_sgpr_workgroup_id_x 1
		.amdhsa_system_sgpr_workgroup_id_y 0
		.amdhsa_system_sgpr_workgroup_id_z 0
		.amdhsa_system_sgpr_workgroup_info 0
		.amdhsa_system_vgpr_workitem_id 2
		.amdhsa_next_free_vgpr 231
		.amdhsa_next_free_sgpr 99
		.amdhsa_accum_offset 232
		.amdhsa_reserve_vcc 1
		.amdhsa_float_round_mode_32 0
		.amdhsa_float_round_mode_16_64 0
		.amdhsa_float_denorm_mode_32 3
		.amdhsa_float_denorm_mode_16_64 3
		.amdhsa_dx10_clamp 1
		.amdhsa_ieee_mode 1
		.amdhsa_fp16_overflow 0
		.amdhsa_tg_split 0
		.amdhsa_exception_fp_ieee_invalid_op 0
		.amdhsa_exception_fp_denorm_src 0
		.amdhsa_exception_fp_ieee_div_zero 0
		.amdhsa_exception_fp_ieee_overflow 0
		.amdhsa_exception_fp_ieee_underflow 0
		.amdhsa_exception_fp_ieee_inexact 0
		.amdhsa_exception_int_div_zero 0
	.end_amdhsa_kernel

amdhsa.kernels:
  - .agpr_count:     0
    .args:
      - .offset:         0
        .size:           120
        .value_kind:     by_value
      - .offset:         120
        .size:           4
        .value_kind:     hidden_block_count_x
      - .offset:         124
        .size:           4
        .value_kind:     hidden_block_count_y
      - .offset:         128
        .size:           4
        .value_kind:     hidden_block_count_z
      - .offset:         132
        .size:           2
        .value_kind:     hidden_group_size_x
      - .offset:         134
        .size:           2
        .value_kind:     hidden_group_size_y
      - .offset:         136
        .size:           2
        .value_kind:     hidden_group_size_z
      - .offset:         138
        .size:           2
        .value_kind:     hidden_remainder_x
      - .offset:         140
        .size:           2
        .value_kind:     hidden_remainder_y
      - .offset:         142
        .size:           2
        .value_kind:     hidden_remainder_z
      - .offset:         160
        .size:           8
        .value_kind:     hidden_global_offset_x
      - .offset:         168
        .size:           8
        .value_kind:     hidden_global_offset_y
      - .offset:         176
        .size:           8
        .value_kind:     hidden_global_offset_z
      - .offset:         184
        .size:           2
        .value_kind:     hidden_grid_dims
      - .offset:         208
        .size:           8
        .value_kind:     hidden_multigrid_sync_arg
      - .offset:         240
        .size:           4
        .value_kind:     hidden_dynamic_lds_size
    .group_segment_fixed_size: 0
    .kernarg_segment_align: 8
    .kernarg_segment_size: 376
    .language:       OpenCL C
    .language_version:
      - 2
      - 0
    .max_flat_workgroup_size: 512
    .name:           _Z8yoco_fwd4Args
    .private_segment_fixed_size: 0
    .sgpr_count:     105
    .sgpr_spill_count: 3
    .symbol:         _Z8yoco_fwd4Args.kd
    .uniform_work_group_size: 1
    .uses_dynamic_stack: false
    .vgpr_count:     231
    .vgpr_spill_count: 0
    .wavefront_size: 64
